# FFN-up epilogue: sequence-end (pos==L-1) conv fix-up of each store site grouped behind one uniform skip branch
# baseline (speedup 1.0000x reference)
.LBB0_757:
	v_lshl_or_b32 v152, s12, 7, v222
	v_cmp_gt_i32_e32 vcc, s35, v229
	s_add_i32 s24, s35, -16
	v_ashrrev_i32_e32 v153, 31, v152
	s_and_b64 s[50:51], s[84:85], vcc
	v_add_u32_e32 v155, s94, v229
	v_xor_b32_e32 v159, 0x80000000, v91
	v_xor_b32_e32 v158, 0x80000000, v90
	v_xor_b32_e32 v157, 0x80000000, v83
	v_xor_b32_e32 v156, 0x80000000, v82
	s_and_saveexec_b64 s[12:13], s[50:51]
	s_cbranch_execz .LBB0_759
	s_cmp_ge_i32 s25, s24
	v_pk_fma_f32 v[144:145], v[80:81], v[200:201], v[144:145]
	s_cselect_b64 s[14:15], -1, 0
	v_pk_add_f32 v[144:145], v[84:85], v[144:145]
	v_pk_fma_f32 v[148:149], v[88:89], v[204:205], v[148:149]
	v_pk_fma_f32 v[146:147], v[82:83], v[202:203], v[146:147]
	v_pk_fma_f32 v[150:151], v[90:91], v[206:207], v[150:151]
	v_pk_add_f32 v[148:149], v[92:93], v[148:149]
	v_pk_add_f32 v[146:147], v[86:87], v[146:147]
	v_pk_add_f32 v[150:151], v[94:95], v[150:151]
	s_mov_b32 s16, 0x3f35f0e3
	s_mov_b32 s18, 0xbe11a98e
	s_mov_b32 s28, 0x3e027906
	s_cmp_eq_u64 s[14:15], 0
	s_cbranch_scc1 .Lffe_759
	v_cmp_eq_u32_e32 vcc, s37, v229
	s_nop 1
	s_and_b64 vcc, s[14:15], vcc
	v_pk_fma_f32 v[200:201], v[80:81], v[200:201], v[144:145] neg_lo:[1,0,0] neg_hi:[1,0,0]
	s_nop 0
	v_cndmask_b32_e32 v145, v145, v201, vcc
	v_cndmask_b32_e32 v144, v144, v200, vcc
	v_pk_fma_f32 v[204:205], v[88:89], v[204:205], v[148:149] neg_lo:[1,0,0] neg_hi:[1,0,0]
	v_pk_fma_f32 v[202:203], v[156:157], v[202:203], v[146:147]
	v_pk_fma_f32 v[206:207], v[158:159], v[206:207], v[150:151]
	v_cndmask_b32_e32 v149, v149, v205, vcc
	v_cndmask_b32_e32 v148, v148, v204, vcc
	v_cndmask_b32_e32 v146, v146, v202, vcc
	v_cndmask_b32_e32 v151, v151, v207, vcc
	v_cndmask_b32_e32 v150, v150, v206, vcc
	v_cndmask_b32_e32 v147, v147, v203, vcc
.Lffe_759:
	v_fma_f32 v154, |v144|, s74, 1.0
	v_fma_f32 v201, |v145|, s74, 1.0
	v_rcp_f32_e32 v200, v154
	v_rcp_f32_e32 v201, v201
	v_mul_f32_e32 v154, v144, v144
	v_mul_f32_e32 v154, 0xbf38aa3b, v154
	s_mov_b32 s14, 0xbf3a00e3
	v_exp_f32_e32 v202, v154
	v_mov_b64_e32 v[204:205], s[14:15]
	s_mov_b32 s14, 0x3f07dc22
	v_mul_f32_e32 v154, v145, v145
	v_pk_fma_f32 v[206:207], v[200:201], s[14:15], v[204:205] op_sel_hi:[1,0,0]
	v_mul_f32_e32 v154, 0xbf38aa3b, v154
	v_exp_f32_e32 v203, v154
	v_pk_fma_f32 v[206:207], v[200:201], v[206:207], s[16:17] op_sel_hi:[1,1,0]
	s_nop 0
	v_pk_fma_f32 v[206:207], v[200:201], v[206:207], s[18:19] op_sel_hi:[1,1,0]
	s_nop 0
	v_pk_fma_f32 v[206:207], v[200:201], v[206:207], s[28:29] op_sel_hi:[1,1,0]
	v_cmp_gt_f32_e32 vcc, 0, v145
	v_pk_mul_f32 v[200:201], v[200:201], v[206:207]
	s_nop 0
	v_pk_mul_f32 v[200:201], v[202:203], v[200:201]
	s_nop 0
	v_pk_mul_f32 v[202:203], v[144:145], v[200:201]
	v_pk_fma_f32 v[200:201], v[144:145], v[200:201], v[144:145] neg_lo:[1,0,0] neg_hi:[1,0,0]
	s_nop 0
	v_cndmask_b32_e32 v145, v201, v203, vcc
	v_cmp_gt_f32_e32 vcc, 0, v144
	s_nop 1
	v_cndmask_b32_e32 v144, v200, v202, vcc
	v_pk_mul_f32 v[144:145], v[148:149], v[144:145]
	v_cmp_gt_f32_e32 vcc, 0, v147
	v_cvt_pk_bf16_f32 v144, v144, v145
	v_fma_f32 v145, |v146|, s74, 1.0
	v_rcp_f32_e32 v148, v145
	v_fma_f32 v145, |v147|, s74, 1.0
	v_rcp_f32_e32 v149, v145
	v_mul_f32_e32 v145, v146, v146
	v_mul_f32_e32 v145, 0xbf38aa3b, v145
	v_exp_f32_e32 v200, v145
	v_mul_f32_e32 v145, v147, v147
	v_pk_fma_f32 v[202:203], v[148:149], s[14:15], v[204:205] op_sel_hi:[1,0,0]
	v_mul_f32_e32 v145, 0xbf38aa3b, v145
	v_exp_f32_e32 v201, v145
	v_pk_fma_f32 v[202:203], v[148:149], v[202:203], s[16:17] op_sel_hi:[1,1,0]
	s_movk_i32 s14, 0x1600
	v_pk_fma_f32 v[202:203], v[148:149], v[202:203], s[18:19] op_sel_hi:[1,1,0]
	s_nop 0
	v_pk_fma_f32 v[202:203], v[148:149], v[202:203], s[28:29] op_sel_hi:[1,1,0]
	s_nop 0
	v_pk_mul_f32 v[148:149], v[148:149], v[202:203]
	s_nop 0
	v_pk_mul_f32 v[148:149], v[200:201], v[148:149]
	s_nop 0
	v_pk_mul_f32 v[200:201], v[146:147], v[148:149]
	v_pk_fma_f32 v[148:149], v[146:147], v[148:149], v[146:147] neg_lo:[1,0,0] neg_hi:[1,0,0]
	s_nop 0
	v_cndmask_b32_e32 v147, v149, v201, vcc
	v_cmp_gt_f32_e32 vcc, 0, v146
	s_nop 1
	v_cndmask_b32_e32 v146, v148, v200, vcc
	v_pk_mul_f32 v[146:147], v[150:151], v[146:147]
	s_nop 0
	v_cvt_pk_bf16_f32 v145, v146, v147
	v_mov_b64_e32 v[146:147], s[26:27]
	v_mad_i64_i32 v[146:147], s[14:15], v155, s14, v[146:147]
	v_lshl_add_u64 v[146:147], v[152:153], 1, v[146:147]
	global_store_dwordx2 v[146:147], v[144:145], off

.LBB0_763:
	s_add_i32 s23, s25, 16
	v_cmp_gt_i32_e64 s[12:13], s35, v228
	v_add_u32_e32 v145, s94, v228
	s_and_saveexec_b64 s[14:15], s[12:13]
	s_cbranch_execz .LBB0_765
	s_cmp_lt_i32 s23, s35
	s_cselect_b64 s[16:17], -1, 0
	s_cmp_ge_i32 s23, s24
	s_cselect_b64 s[18:19], -1, 0
	v_pk_fma_f32 v[140:141], v[88:89], v[212:213], v[140:141]
	s_and_b64 s[16:17], s[16:17], s[18:19]
	v_pk_fma_f32 v[142:143], v[90:91], v[214:215], v[142:143]
	v_pk_add_f32 v[140:141], v[92:93], v[140:141]
	v_pk_fma_f32 v[136:137], v[80:81], v[208:209], v[136:137]
	v_pk_add_f32 v[142:143], v[94:95], v[142:143]
	v_pk_fma_f32 v[138:139], v[82:83], v[210:211], v[138:139]
	v_pk_add_f32 v[136:137], v[84:85], v[136:137]
	v_pk_add_f32 v[138:139], v[86:87], v[138:139]
	s_mov_b32 s18, 0x3f35f0e3
	s_mov_b32 s28, 0xbe11a98e
	s_mov_b32 s54, 0x3e027906
	s_cmp_eq_u64 s[16:17], 0
	s_cbranch_scc1 .Lffe_765
	v_cmp_eq_u32_e32 vcc, s37, v228
	v_pk_fma_f32 v[148:149], v[88:89], v[212:213], v[140:141] neg_lo:[1,0,0] neg_hi:[1,0,0]
	s_nop 0
	s_and_b64 vcc, s[16:17], vcc
	v_pk_fma_f32 v[146:147], v[158:159], v[214:215], v[142:143]
	v_cndmask_b32_e32 v141, v141, v149, vcc
	v_cndmask_b32_e32 v140, v140, v148, vcc
	v_pk_fma_f32 v[148:149], v[80:81], v[208:209], v[136:137] neg_lo:[1,0,0] neg_hi:[1,0,0]
	v_cndmask_b32_e32 v143, v143, v147, vcc
	v_cndmask_b32_e32 v142, v142, v146, vcc
	v_pk_fma_f32 v[146:147], v[156:157], v[210:211], v[138:139]
	v_cndmask_b32_e32 v137, v137, v149, vcc
	v_cndmask_b32_e32 v136, v136, v148, vcc
	v_cndmask_b32_e32 v139, v139, v147, vcc
	v_cndmask_b32_e32 v138, v138, v146, vcc
.Lffe_765:
	v_fma_f32 v144, |v136|, s74, 1.0
	v_fma_f32 v147, |v137|, s74, 1.0
	v_rcp_f32_e32 v146, v144
	v_rcp_f32_e32 v147, v147
	v_mul_f32_e32 v144, v136, v136
	v_mul_f32_e32 v144, 0xbf38aa3b, v144
	s_mov_b32 s16, 0xbf3a00e3
	v_exp_f32_e32 v148, v144
	v_mov_b64_e32 v[150:151], s[16:17]
	s_mov_b32 s16, 0x3f07dc22
	v_mul_f32_e32 v144, v137, v137
	v_pk_fma_f32 v[208:209], v[146:147], s[16:17], v[150:151] op_sel_hi:[1,0,0]
	v_mul_f32_e32 v144, 0xbf38aa3b, v144
	v_exp_f32_e32 v149, v144
	v_pk_fma_f32 v[208:209], v[146:147], v[208:209], s[18:19] op_sel_hi:[1,1,0]
	s_nop 0
	v_pk_fma_f32 v[208:209], v[146:147], v[208:209], s[28:29] op_sel_hi:[1,1,0]
	s_nop 0
	v_pk_fma_f32 v[208:209], v[146:147], v[208:209], s[54:55] op_sel_hi:[1,1,0]
	v_cmp_gt_f32_e32 vcc, 0, v137
	v_pk_mul_f32 v[146:147], v[146:147], v[208:209]
	s_nop 0
	v_pk_mul_f32 v[146:147], v[148:149], v[146:147]
	s_nop 0
	v_pk_mul_f32 v[148:149], v[136:137], v[146:147]
	v_pk_fma_f32 v[146:147], v[136:137], v[146:147], v[136:137] neg_lo:[1,0,0] neg_hi:[1,0,0]
	s_nop 0
	v_cndmask_b32_e32 v137, v147, v149, vcc
	v_cmp_gt_f32_e32 vcc, 0, v136
	s_nop 1
	v_cndmask_b32_e32 v136, v146, v148, vcc
	v_pk_mul_f32 v[136:137], v[140:141], v[136:137]
	v_cmp_gt_f32_e32 vcc, 0, v139
	v_cvt_pk_bf16_f32 v136, v136, v137
	v_fma_f32 v137, |v138|, s74, 1.0
	v_rcp_f32_e32 v140, v137
	v_fma_f32 v137, |v139|, s74, 1.0
	v_rcp_f32_e32 v141, v137
	v_mul_f32_e32 v137, v138, v138
	v_mul_f32_e32 v137, 0xbf38aa3b, v137
	v_exp_f32_e32 v146, v137
	v_mul_f32_e32 v137, v139, v139
	v_pk_fma_f32 v[148:149], v[140:141], s[16:17], v[150:151] op_sel_hi:[1,0,0]
	v_mul_f32_e32 v137, 0xbf38aa3b, v137
	v_exp_f32_e32 v147, v137
	v_pk_fma_f32 v[148:149], v[140:141], v[148:149], s[18:19] op_sel_hi:[1,1,0]
	s_movk_i32 s16, 0x1600
	v_pk_fma_f32 v[148:149], v[140:141], v[148:149], s[28:29] op_sel_hi:[1,1,0]
	s_nop 0
	v_pk_fma_f32 v[148:149], v[140:141], v[148:149], s[54:55] op_sel_hi:[1,1,0]
	s_nop 0
	v_pk_mul_f32 v[140:141], v[140:141], v[148:149]
	s_nop 0
	v_pk_mul_f32 v[140:141], v[146:147], v[140:141]
	s_nop 0
	v_pk_mul_f32 v[146:147], v[138:139], v[140:141]
	v_pk_fma_f32 v[140:141], v[138:139], v[140:141], v[138:139] neg_lo:[1,0,0] neg_hi:[1,0,0]
	s_nop 0
	v_cndmask_b32_e32 v139, v141, v147, vcc
	v_cmp_gt_f32_e32 vcc, 0, v138
	s_nop 1
	v_cndmask_b32_e32 v138, v140, v146, vcc
	v_pk_mul_f32 v[138:139], v[142:143], v[138:139]
	s_nop 0
	v_cvt_pk_bf16_f32 v137, v138, v139
	v_mov_b64_e32 v[138:139], s[26:27]
	v_mad_i64_i32 v[138:139], s[16:17], v145, s16, v[138:139]
	v_lshl_add_u64 v[138:139], v[152:153], 1, v[138:139]
	global_store_dwordx2 v[138:139], v[136:137], off

.LBB0_769:
	s_add_i32 s67, s25, 32
	v_cmp_gt_i32_e64 s[14:15], s35, v211
	v_add_u32_e32 v210, s94, v211
	s_and_saveexec_b64 s[16:17], s[14:15]
	s_cbranch_execz .LBB0_771
	s_cmp_lt_i32 s67, s35
	s_cselect_b64 s[18:19], -1, 0
	s_cmp_ge_i32 s67, s24
	s_cselect_b64 s[78:79], -1, 0
	v_pk_fma_f32 v[132:133], v[88:89], v[196:197], v[132:133]
	s_and_b64 s[18:19], s[18:19], s[78:79]
	v_pk_fma_f32 v[134:135], v[90:91], v[198:199], v[134:135]
	v_pk_add_f32 v[132:133], v[92:93], v[132:133]
	v_pk_fma_f32 v[128:129], v[80:81], v[192:193], v[128:129]
	v_pk_add_f32 v[134:135], v[94:95], v[134:135]
	v_pk_fma_f32 v[130:131], v[82:83], v[194:195], v[130:131]
	v_pk_add_f32 v[128:129], v[84:85], v[128:129]
	v_pk_add_f32 v[130:131], v[86:87], v[130:131]
	s_mov_b32 s60, 0x3f35f0e3
	s_mov_b32 s28, 0xbe11a98e
	s_mov_b32 s64, 0x3e027906
	s_cmp_eq_u64 s[18:19], 0
	s_cbranch_scc1 .Lffe_771
	v_cmp_eq_u32_e32 vcc, s37, v211
	v_pk_fma_f32 v[138:139], v[88:89], v[196:197], v[132:133] neg_lo:[1,0,0] neg_hi:[1,0,0]
	s_nop 0
	s_and_b64 vcc, s[18:19], vcc
	v_pk_fma_f32 v[136:137], v[158:159], v[198:199], v[134:135]
	v_cndmask_b32_e32 v133, v133, v139, vcc
	v_cndmask_b32_e32 v132, v132, v138, vcc
	v_pk_fma_f32 v[138:139], v[80:81], v[192:193], v[128:129] neg_lo:[1,0,0] neg_hi:[1,0,0]
	v_cndmask_b32_e32 v135, v135, v137, vcc
	v_cndmask_b32_e32 v134, v134, v136, vcc
	v_pk_fma_f32 v[136:137], v[156:157], v[194:195], v[130:131]
	v_cndmask_b32_e32 v129, v129, v139, vcc
	v_cndmask_b32_e32 v128, v128, v138, vcc
	v_cndmask_b32_e32 v131, v131, v137, vcc
	v_cndmask_b32_e32 v130, v130, v136, vcc
.Lffe_771:
	v_fma_f32 v136, |v128|, s74, 1.0
	v_fma_f32 v137, |v129|, s74, 1.0
	v_rcp_f32_e32 v136, v136
	v_rcp_f32_e32 v137, v137
	s_mov_b32 s18, 0xbf3a00e3
	v_mul_f32_e32 v138, v128, v128
	v_mov_b64_e32 v[140:141], s[18:19]
	s_mov_b32 s18, 0x3f07dc22
	v_mul_f32_e32 v139, v129, v129
	v_mul_f32_e32 v138, 0xbf38aa3b, v138
	v_pk_fma_f32 v[142:143], v[136:137], s[18:19], v[140:141] op_sel_hi:[1,0,0]
	v_mul_f32_e32 v139, 0xbf38aa3b, v139
	v_exp_f32_e32 v138, v138
	v_exp_f32_e32 v139, v139
	v_pk_fma_f32 v[142:143], v[136:137], v[142:143], s[60:61] op_sel_hi:[1,1,0]
	s_nop 0
	v_pk_fma_f32 v[142:143], v[136:137], v[142:143], s[28:29] op_sel_hi:[1,1,0]
	s_nop 0
	v_pk_fma_f32 v[142:143], v[136:137], v[142:143], s[64:65] op_sel_hi:[1,1,0]
	v_cmp_gt_f32_e32 vcc, 0, v129
	v_pk_mul_f32 v[136:137], v[136:137], v[142:143]
	s_nop 0
	v_pk_mul_f32 v[136:137], v[138:139], v[136:137]
	s_nop 0
	v_pk_mul_f32 v[138:139], v[128:129], v[136:137]
	v_pk_fma_f32 v[136:137], v[128:129], v[136:137], v[128:129] neg_lo:[1,0,0] neg_hi:[1,0,0]
	s_nop 0
	v_cndmask_b32_e32 v129, v137, v139, vcc
	v_cmp_gt_f32_e32 vcc, 0, v128
	s_nop 1
	v_cndmask_b32_e32 v128, v136, v138, vcc
	v_pk_mul_f32 v[128:129], v[132:133], v[128:129]
	v_cmp_gt_f32_e32 vcc, 0, v131
	v_cvt_pk_bf16_f32 v128, v128, v129
	v_fma_f32 v129, |v130|, s74, 1.0
	v_rcp_f32_e32 v132, v129
	v_fma_f32 v129, |v131|, s74, 1.0
	v_rcp_f32_e32 v133, v129
	v_mul_f32_e32 v129, v130, v130
	v_mul_f32_e32 v129, 0xbf38aa3b, v129
	v_exp_f32_e32 v136, v129
	v_mul_f32_e32 v129, v131, v131
	v_pk_fma_f32 v[138:139], v[132:133], s[18:19], v[140:141] op_sel_hi:[1,0,0]
	v_mul_f32_e32 v129, 0xbf38aa3b, v129
	v_exp_f32_e32 v137, v129
	v_pk_fma_f32 v[138:139], v[132:133], v[138:139], s[60:61] op_sel_hi:[1,1,0]
	s_movk_i32 s18, 0x1600
	v_pk_fma_f32 v[138:139], v[132:133], v[138:139], s[28:29] op_sel_hi:[1,1,0]
	s_nop 0
	v_pk_fma_f32 v[138:139], v[132:133], v[138:139], s[64:65] op_sel_hi:[1,1,0]
	s_nop 0
	v_pk_mul_f32 v[132:133], v[132:133], v[138:139]
	s_nop 0
	v_pk_mul_f32 v[132:133], v[136:137], v[132:133]
	s_nop 0
	v_pk_mul_f32 v[136:137], v[130:131], v[132:133]
	v_pk_fma_f32 v[132:133], v[130:131], v[132:133], v[130:131] neg_lo:[1,0,0] neg_hi:[1,0,0]
	s_nop 0
	v_cndmask_b32_e32 v131, v133, v137, vcc
	v_cmp_gt_f32_e32 vcc, 0, v130
	s_nop 1
	v_cndmask_b32_e32 v130, v132, v136, vcc
	v_pk_mul_f32 v[130:131], v[134:135], v[130:131]
	s_nop 0
	v_cvt_pk_bf16_f32 v129, v130, v131
	v_mov_b64_e32 v[130:131], s[26:27]
	v_mad_i64_i32 v[130:131], s[18:19], v210, s18, v[130:131]
	v_lshl_add_u64 v[130:131], v[152:153], 1, v[130:131]
	global_store_dwordx2 v[130:131], v[128:129], off

.LBB0_775:
	v_readlane_b32 s8, v242, 27
	v_cmp_gt_i32_e32 vcc, s35, v212
	v_readlane_b32 s9, v242, 28
	s_add_i32 s69, s25, 48
	s_and_b64 s[80:81], s[8:9], vcc
	v_add_u32_e32 v200, s94, v212
	s_and_saveexec_b64 s[16:17], s[80:81]
	s_cbranch_execz .LBB0_777
	s_cmp_lt_i32 s69, s35
	s_cselect_b64 s[18:19], -1, 0
	s_cmp_ge_i32 s69, s24
	s_cselect_b64 s[82:83], -1, 0
	v_pk_fma_f32 v[132:133], v[88:89], v[196:197], v[132:133]
	s_and_b64 s[18:19], s[18:19], s[82:83]
	v_pk_fma_f32 v[134:135], v[90:91], v[198:199], v[134:135]
	v_pk_add_f32 v[132:133], v[92:93], v[132:133]
	v_pk_fma_f32 v[128:129], v[80:81], v[192:193], v[128:129]
	v_pk_add_f32 v[134:135], v[94:95], v[134:135]
	v_pk_fma_f32 v[130:131], v[82:83], v[194:195], v[130:131]
	v_pk_add_f32 v[128:129], v[84:85], v[128:129]
	v_pk_add_f32 v[130:131], v[86:87], v[130:131]
	s_mov_b32 s60, 0x3f35f0e3
	s_mov_b32 s28, 0xbe11a98e
	s_mov_b32 s64, 0x3e027906
	s_cmp_eq_u64 s[18:19], 0
	s_cbranch_scc1 .Lffe_777
	v_cmp_eq_u32_e32 vcc, s37, v212
	v_pk_fma_f32 v[138:139], v[88:89], v[196:197], v[132:133] neg_lo:[1,0,0] neg_hi:[1,0,0]
	s_nop 0
	s_and_b64 vcc, s[18:19], vcc
	v_pk_fma_f32 v[136:137], v[158:159], v[198:199], v[134:135]
	v_cndmask_b32_e32 v133, v133, v139, vcc
	v_cndmask_b32_e32 v132, v132, v138, vcc
	v_pk_fma_f32 v[138:139], v[80:81], v[192:193], v[128:129] neg_lo:[1,0,0] neg_hi:[1,0,0]
	v_cndmask_b32_e32 v135, v135, v137, vcc
	v_cndmask_b32_e32 v134, v134, v136, vcc
	v_pk_fma_f32 v[136:137], v[156:157], v[194:195], v[130:131]
	v_cndmask_b32_e32 v129, v129, v139, vcc
	v_cndmask_b32_e32 v128, v128, v138, vcc
	v_cndmask_b32_e32 v131, v131, v137, vcc
	v_cndmask_b32_e32 v130, v130, v136, vcc
.Lffe_777:
	v_fma_f32 v136, |v128|, s74, 1.0
	v_fma_f32 v137, |v129|, s74, 1.0
	v_rcp_f32_e32 v136, v136
	v_rcp_f32_e32 v137, v137
	s_mov_b32 s18, 0xbf3a00e3
	v_mul_f32_e32 v138, v128, v128
	v_mov_b64_e32 v[140:141], s[18:19]
	s_mov_b32 s18, 0x3f07dc22
	v_mul_f32_e32 v139, v129, v129
	v_mul_f32_e32 v138, 0xbf38aa3b, v138
	v_pk_fma_f32 v[142:143], v[136:137], s[18:19], v[140:141] op_sel_hi:[1,0,0]
	v_mul_f32_e32 v139, 0xbf38aa3b, v139
	v_exp_f32_e32 v138, v138
	v_exp_f32_e32 v139, v139
	v_pk_fma_f32 v[142:143], v[136:137], v[142:143], s[60:61] op_sel_hi:[1,1,0]
	s_nop 0
	v_pk_fma_f32 v[142:143], v[136:137], v[142:143], s[28:29] op_sel_hi:[1,1,0]
	s_nop 0
	v_pk_fma_f32 v[142:143], v[136:137], v[142:143], s[64:65] op_sel_hi:[1,1,0]
	v_cmp_gt_f32_e32 vcc, 0, v129
	v_pk_mul_f32 v[136:137], v[136:137], v[142:143]
	s_nop 0
	v_pk_mul_f32 v[136:137], v[138:139], v[136:137]
	s_nop 0
	v_pk_mul_f32 v[138:139], v[128:129], v[136:137]
	v_pk_fma_f32 v[136:137], v[128:129], v[136:137], v[128:129] neg_lo:[1,0,0] neg_hi:[1,0,0]
	s_nop 0
	v_cndmask_b32_e32 v129, v137, v139, vcc
	v_cmp_gt_f32_e32 vcc, 0, v128
	s_nop 1
	v_cndmask_b32_e32 v128, v136, v138, vcc
	v_pk_mul_f32 v[128:129], v[132:133], v[128:129]
	v_cmp_gt_f32_e32 vcc, 0, v131
	v_cvt_pk_bf16_f32 v128, v128, v129
	v_fma_f32 v129, |v130|, s74, 1.0
	v_rcp_f32_e32 v132, v129
	v_fma_f32 v129, |v131|, s74, 1.0
	v_rcp_f32_e32 v133, v129
	v_mul_f32_e32 v129, v130, v130
	v_mul_f32_e32 v129, 0xbf38aa3b, v129
	v_exp_f32_e32 v136, v129
	v_mul_f32_e32 v129, v131, v131
	v_pk_fma_f32 v[138:139], v[132:133], s[18:19], v[140:141] op_sel_hi:[1,0,0]
	v_mul_f32_e32 v129, 0xbf38aa3b, v129
	v_exp_f32_e32 v137, v129
	v_pk_fma_f32 v[138:139], v[132:133], v[138:139], s[60:61] op_sel_hi:[1,1,0]
	s_movk_i32 s18, 0x1600
	v_pk_fma_f32 v[138:139], v[132:133], v[138:139], s[28:29] op_sel_hi:[1,1,0]
	s_nop 0
	v_pk_fma_f32 v[138:139], v[132:133], v[138:139], s[64:65] op_sel_hi:[1,1,0]
	s_nop 0
	v_pk_mul_f32 v[132:133], v[132:133], v[138:139]
	s_nop 0
	v_pk_mul_f32 v[132:133], v[136:137], v[132:133]
	s_nop 0
	v_pk_mul_f32 v[136:137], v[130:131], v[132:133]
	v_pk_fma_f32 v[132:133], v[130:131], v[132:133], v[130:131] neg_lo:[1,0,0] neg_hi:[1,0,0]
	s_nop 0
	v_cndmask_b32_e32 v131, v133, v137, vcc
	v_cmp_gt_f32_e32 vcc, 0, v130
	s_nop 1
	v_cndmask_b32_e32 v130, v132, v136, vcc
	v_pk_mul_f32 v[130:131], v[134:135], v[130:131]
	s_nop 0
	v_cvt_pk_bf16_f32 v129, v130, v131
	v_mov_b64_e32 v[130:131], s[26:27]
	v_mad_i64_i32 v[130:131], s[18:19], v200, s18, v[130:131]
	v_lshl_add_u64 v[130:131], v[152:153], 1, v[130:131]
	global_store_dwordx2 v[130:131], v[128:129], off

.LBB0_781:
	v_cmp_gt_i32_e32 vcc, s35, v198
	s_mov_b64 s[10:11], s[84:85]
	s_and_b64 s[84:85], s[84:85], vcc
	v_add_u32_e32 v105, s94, v198
	s_and_saveexec_b64 s[16:17], s[84:85]
	s_cbranch_execz .LBB0_783
	s_cmp_ge_i32 s22, s24
	v_pk_fma_f32 v[100:101], v[88:89], v[194:195], v[100:101]
	s_cselect_b64 s[18:19], -1, 0
	v_pk_fma_f32 v[102:103], v[90:91], v[196:197], v[102:103]
	v_pk_add_f32 v[100:101], v[92:93], v[100:101]
	v_pk_fma_f32 v[96:97], v[80:81], v[136:137], v[96:97]
	v_pk_add_f32 v[102:103], v[94:95], v[102:103]
	v_pk_fma_f32 v[98:99], v[82:83], v[192:193], v[98:99]
	v_pk_add_f32 v[96:97], v[84:85], v[96:97]
	v_pk_add_f32 v[98:99], v[86:87], v[98:99]
	s_mov_b32 s60, 0x3f35f0e3
	s_mov_b32 s28, 0xbe11a98e
	s_mov_b32 s64, 0x3e027906
	s_cmp_eq_u64 s[18:19], 0
	s_cbranch_scc1 .Lffe_783
	v_cmp_eq_u32_e32 vcc, s37, v198
	v_pk_fma_f32 v[112:113], v[88:89], v[194:195], v[100:101] neg_lo:[1,0,0] neg_hi:[1,0,0]
	s_nop 0
	s_and_b64 vcc, s[18:19], vcc
	v_pk_fma_f32 v[106:107], v[158:159], v[196:197], v[102:103]
	v_cndmask_b32_e32 v101, v101, v113, vcc
	v_cndmask_b32_e32 v100, v100, v112, vcc
	v_pk_fma_f32 v[112:113], v[80:81], v[136:137], v[96:97] neg_lo:[1,0,0] neg_hi:[1,0,0]
	v_cndmask_b32_e32 v103, v103, v107, vcc
	v_cndmask_b32_e32 v102, v102, v106, vcc
	v_pk_fma_f32 v[106:107], v[156:157], v[192:193], v[98:99]
	v_cndmask_b32_e32 v97, v97, v113, vcc
	v_cndmask_b32_e32 v96, v96, v112, vcc
	v_cndmask_b32_e32 v99, v99, v107, vcc
	v_cndmask_b32_e32 v98, v98, v106, vcc
.Lffe_783:
	v_fma_f32 v104, |v96|, s74, 1.0
	v_fma_f32 v107, |v97|, s74, 1.0
	v_rcp_f32_e32 v106, v104
	v_rcp_f32_e32 v107, v107
	v_mul_f32_e32 v104, v96, v96
	v_mul_f32_e32 v104, 0xbf38aa3b, v104
	s_mov_b32 s18, 0xbf3a00e3
	v_exp_f32_e32 v112, v104
	v_mov_b64_e32 v[114:115], s[18:19]
	s_mov_b32 s18, 0x3f07dc22
	v_mul_f32_e32 v104, v97, v97
	v_pk_fma_f32 v[136:137], v[106:107], s[18:19], v[114:115] op_sel_hi:[1,0,0]
	v_mul_f32_e32 v104, 0xbf38aa3b, v104
	v_exp_f32_e32 v113, v104
	v_pk_fma_f32 v[136:137], v[106:107], v[136:137], s[60:61] op_sel_hi:[1,1,0]
	s_nop 0
	v_pk_fma_f32 v[136:137], v[106:107], v[136:137], s[28:29] op_sel_hi:[1,1,0]
	s_nop 0
	v_pk_fma_f32 v[136:137], v[106:107], v[136:137], s[64:65] op_sel_hi:[1,1,0]
	v_cmp_gt_f32_e32 vcc, 0, v97
	v_pk_mul_f32 v[106:107], v[106:107], v[136:137]
	s_nop 0
	v_pk_mul_f32 v[106:107], v[112:113], v[106:107]
	s_nop 0
	v_pk_mul_f32 v[112:113], v[96:97], v[106:107]
	v_pk_fma_f32 v[106:107], v[96:97], v[106:107], v[96:97] neg_lo:[1,0,0] neg_hi:[1,0,0]
	s_nop 0
	v_cndmask_b32_e32 v97, v107, v113, vcc
	v_cmp_gt_f32_e32 vcc, 0, v96
	s_nop 1
	v_cndmask_b32_e32 v96, v106, v112, vcc
	v_pk_mul_f32 v[96:97], v[100:101], v[96:97]
	v_cmp_gt_f32_e32 vcc, 0, v99
	v_cvt_pk_bf16_f32 v96, v96, v97
	v_fma_f32 v97, |v98|, s74, 1.0
	v_rcp_f32_e32 v100, v97
	v_fma_f32 v97, |v99|, s74, 1.0
	v_rcp_f32_e32 v101, v97
	v_mul_f32_e32 v97, v98, v98
	v_mul_f32_e32 v97, 0xbf38aa3b, v97
	v_exp_f32_e32 v106, v97
	v_mul_f32_e32 v97, v99, v99
	v_pk_fma_f32 v[112:113], v[100:101], s[18:19], v[114:115] op_sel_hi:[1,0,0]
	v_mul_f32_e32 v97, 0xbf38aa3b, v97
	v_exp_f32_e32 v107, v97
	v_pk_fma_f32 v[112:113], v[100:101], v[112:113], s[60:61] op_sel_hi:[1,1,0]
	s_movk_i32 s18, 0x1600
	v_pk_fma_f32 v[112:113], v[100:101], v[112:113], s[28:29] op_sel_hi:[1,1,0]
	s_nop 0
	v_pk_fma_f32 v[112:113], v[100:101], v[112:113], s[64:65] op_sel_hi:[1,1,0]
	s_nop 0
	v_pk_mul_f32 v[100:101], v[100:101], v[112:113]
	s_nop 0
	v_pk_mul_f32 v[100:101], v[106:107], v[100:101]
	s_nop 0
	v_pk_mul_f32 v[106:107], v[98:99], v[100:101]
	v_pk_fma_f32 v[100:101], v[98:99], v[100:101], v[98:99] neg_lo:[1,0,0] neg_hi:[1,0,0]
	s_nop 0
	v_cndmask_b32_e32 v99, v101, v107, vcc
	v_cmp_gt_f32_e32 vcc, 0, v98
	s_nop 1
	v_cndmask_b32_e32 v98, v100, v106, vcc
	v_pk_mul_f32 v[98:99], v[102:103], v[98:99]
	s_nop 0
	v_cvt_pk_bf16_f32 v97, v98, v99
	v_mov_b64_e32 v[98:99], s[26:27]
	v_mad_i64_i32 v[98:99], s[18:19], v105, s18, v[98:99]
	v_lshl_add_u64 v[98:99], v[152:153], 1, v[98:99]
	global_store_dwordx2 v[98:99], v[96:97], off

.LBB0_787:
	s_add_i32 s60, s22, 16
	v_cmp_gt_i32_e64 s[16:17], s35, v192
	v_add_u32_e32 v97, s94, v192
	s_and_saveexec_b64 s[18:19], s[16:17]
	s_cbranch_execz .LBB0_789
	s_cmp_lt_i32 s60, s35
	s_cselect_b64 s[88:89], -1, 0
	s_cmp_ge_i32 s60, s24
	s_cselect_b64 s[90:91], -1, 0
	v_pk_fma_f32 v[76:77], v[88:89], v[148:149], v[76:77]
	s_and_b64 s[88:89], s[88:89], s[90:91]
	v_pk_fma_f32 v[78:79], v[90:91], v[150:151], v[78:79]
	v_pk_add_f32 v[76:77], v[92:93], v[76:77]
	v_pk_fma_f32 v[72:73], v[80:81], v[142:143], v[72:73]
	v_pk_add_f32 v[78:79], v[94:95], v[78:79]
	v_pk_fma_f32 v[74:75], v[82:83], v[146:147], v[74:75]
	v_pk_add_f32 v[72:73], v[84:85], v[72:73]
	v_pk_add_f32 v[74:75], v[86:87], v[74:75]
	s_mov_b32 s64, 0xbf3a00e3
	s_nop 0
	v_mov_b64_e32 v[102:103], s[64:65]
	s_mov_b32 s64, 0x3f07dc22
	s_mov_b32 s66, 0x3f35f0e3
	s_mov_b32 s28, 0xbe11a98e
	s_mov_b32 s76, 0x3e027906
	s_cmp_eq_u64 s[88:89], 0
	s_cbranch_scc1 .Lffe_789
	v_cmp_eq_u32_e32 vcc, s37, v192
	v_pk_fma_f32 v[100:101], v[88:89], v[148:149], v[76:77] neg_lo:[1,0,0] neg_hi:[1,0,0]
	s_nop 0
	s_and_b64 vcc, s[88:89], vcc
	v_pk_fma_f32 v[98:99], v[158:159], v[150:151], v[78:79]
	v_cndmask_b32_e32 v77, v77, v101, vcc
	v_cndmask_b32_e32 v76, v76, v100, vcc
	v_pk_fma_f32 v[100:101], v[80:81], v[142:143], v[72:73] neg_lo:[1,0,0] neg_hi:[1,0,0]
	v_cndmask_b32_e32 v79, v79, v99, vcc
	v_cndmask_b32_e32 v78, v78, v98, vcc
	v_pk_fma_f32 v[98:99], v[156:157], v[146:147], v[74:75]
	v_cndmask_b32_e32 v73, v73, v101, vcc
	v_cndmask_b32_e32 v72, v72, v100, vcc
	v_cndmask_b32_e32 v75, v75, v99, vcc
	v_cndmask_b32_e32 v74, v74, v98, vcc
.Lffe_789:
	v_fma_f32 v96, |v72|, s74, 1.0
	v_fma_f32 v99, |v73|, s74, 1.0
	v_rcp_f32_e32 v98, v96
	v_rcp_f32_e32 v99, v99
	v_mul_f32_e32 v96, v72, v72
	v_mul_f32_e32 v96, 0xbf38aa3b, v96
	v_exp_f32_e32 v100, v96
	v_mul_f32_e32 v96, v73, v73
	v_pk_fma_f32 v[142:143], v[98:99], s[64:65], v[102:103] op_sel_hi:[1,0,0]
	v_mul_f32_e32 v96, 0xbf38aa3b, v96
	v_exp_f32_e32 v101, v96
	v_pk_fma_f32 v[142:143], v[98:99], v[142:143], s[66:67] op_sel_hi:[1,1,0]
	s_nop 0
	v_pk_fma_f32 v[142:143], v[98:99], v[142:143], s[28:29] op_sel_hi:[1,1,0]
	s_nop 0
	v_pk_fma_f32 v[142:143], v[98:99], v[142:143], s[76:77] op_sel_hi:[1,1,0]
	v_cmp_gt_f32_e32 vcc, 0, v73
	v_pk_mul_f32 v[98:99], v[98:99], v[142:143]
	s_nop 0
	v_pk_mul_f32 v[98:99], v[100:101], v[98:99]
	s_nop 0
	v_pk_mul_f32 v[100:101], v[72:73], v[98:99]
	v_pk_fma_f32 v[98:99], v[72:73], v[98:99], v[72:73] neg_lo:[1,0,0] neg_hi:[1,0,0]
	s_nop 0
	v_cndmask_b32_e32 v73, v99, v101, vcc
	v_cmp_gt_f32_e32 vcc, 0, v72
	s_nop 1
	v_cndmask_b32_e32 v72, v98, v100, vcc
	v_pk_mul_f32 v[72:73], v[76:77], v[72:73]
	v_cmp_gt_f32_e32 vcc, 0, v75
	v_cvt_pk_bf16_f32 v72, v72, v73
	v_fma_f32 v73, |v74|, s74, 1.0
	v_rcp_f32_e32 v76, v73
	v_fma_f32 v73, |v75|, s74, 1.0
	v_rcp_f32_e32 v77, v73
	v_mul_f32_e32 v73, v74, v74
	v_mul_f32_e32 v73, 0xbf38aa3b, v73
	v_exp_f32_e32 v98, v73
	v_mul_f32_e32 v73, v75, v75
	v_pk_fma_f32 v[100:101], v[76:77], s[64:65], v[102:103] op_sel_hi:[1,0,0]
	v_mul_f32_e32 v73, 0xbf38aa3b, v73
	v_exp_f32_e32 v99, v73
	v_pk_fma_f32 v[100:101], v[76:77], v[100:101], s[66:67] op_sel_hi:[1,1,0]
	s_movk_i32 s64, 0x1600
	v_pk_fma_f32 v[100:101], v[76:77], v[100:101], s[28:29] op_sel_hi:[1,1,0]
	s_nop 0
	v_pk_fma_f32 v[100:101], v[76:77], v[100:101], s[76:77] op_sel_hi:[1,1,0]
	s_nop 0
	v_pk_mul_f32 v[76:77], v[76:77], v[100:101]
	s_nop 0
	v_pk_mul_f32 v[76:77], v[98:99], v[76:77]
	s_nop 0
	v_pk_mul_f32 v[98:99], v[74:75], v[76:77]
	v_pk_fma_f32 v[76:77], v[74:75], v[76:77], v[74:75] neg_lo:[1,0,0] neg_hi:[1,0,0]
	s_nop 0
	v_cndmask_b32_e32 v75, v77, v99, vcc
	v_cmp_gt_f32_e32 vcc, 0, v74
	s_nop 1
	v_cndmask_b32_e32 v74, v76, v98, vcc
	v_pk_mul_f32 v[74:75], v[78:79], v[74:75]
	s_nop 0
	v_cvt_pk_bf16_f32 v73, v74, v75
	v_mov_b64_e32 v[74:75], s[26:27]
	v_mad_i64_i32 v[74:75], s[88:89], v97, s64, v[74:75]
	v_lshl_add_u64 v[74:75], v[152:153], 1, v[74:75]
	global_store_dwordx2 v[74:75], v[72:73], off

.LBB0_793:
	s_add_i32 s64, s22, 32
	v_cmp_gt_i32_e64 s[18:19], s35, v147
	v_add_u32_e32 v146, s94, v147
	s_and_saveexec_b64 s[90:91], s[18:19]
	s_cbranch_execz .LBB0_795
	s_cmp_lt_i32 s64, s35
	s_cselect_b64 s[92:93], -1, 0
	s_cmp_ge_i32 s64, s24
	s_cselect_b64 vcc, -1, 0
	v_pk_fma_f32 v[68:69], v[88:89], v[138:139], v[68:69]
	s_and_b64 s[92:93], s[92:93], vcc
	v_pk_fma_f32 v[70:71], v[90:91], v[140:141], v[70:71]
	v_pk_add_f32 v[68:69], v[92:93], v[68:69]
	v_pk_fma_f32 v[64:65], v[80:81], v[132:133], v[64:65]
	v_pk_add_f32 v[70:71], v[94:95], v[70:71]
	v_pk_fma_f32 v[66:67], v[82:83], v[134:135], v[66:67]
	v_pk_add_f32 v[64:65], v[84:85], v[64:65]
	v_pk_add_f32 v[66:67], v[86:87], v[66:67]
	s_mov_b32 s66, 0xbf3a00e3
	s_nop 0
	v_mov_b64_e32 v[76:77], s[66:67]
	s_mov_b32 s66, 0x3f07dc22
	s_mov_b32 s28, 0xbe11a98e
	s_mov_b32 s76, 0x3e027906
	s_cmp_eq_u64 s[92:93], 0
	s_cbranch_scc1 .Lffe_795
	v_cmp_eq_u32_e32 vcc, s37, v147
	v_pk_fma_f32 v[74:75], v[88:89], v[138:139], v[68:69] neg_lo:[1,0,0] neg_hi:[1,0,0]
	s_nop 0
	s_and_b64 vcc, s[92:93], vcc
	v_pk_fma_f32 v[72:73], v[158:159], v[140:141], v[70:71]
	v_cndmask_b32_e32 v69, v69, v75, vcc
	v_cndmask_b32_e32 v68, v68, v74, vcc
	v_pk_fma_f32 v[74:75], v[80:81], v[132:133], v[64:65] neg_lo:[1,0,0] neg_hi:[1,0,0]
	v_cndmask_b32_e32 v71, v71, v73, vcc
	v_cndmask_b32_e32 v70, v70, v72, vcc
	v_pk_fma_f32 v[72:73], v[156:157], v[134:135], v[66:67]
	v_cndmask_b32_e32 v65, v65, v75, vcc
	v_cndmask_b32_e32 v64, v64, v74, vcc
	v_cndmask_b32_e32 v67, v67, v73, vcc
	v_cndmask_b32_e32 v66, v66, v72, vcc
.Lffe_795:
	v_fma_f32 v72, |v64|, s74, 1.0
	v_fma_f32 v73, |v65|, s74, 1.0
	v_rcp_f32_e32 v72, v72
	v_rcp_f32_e32 v73, v73
	v_mul_f32_e32 v74, v64, v64
	v_mul_f32_e32 v75, v65, v65
	v_mul_f32_e32 v74, 0xbf38aa3b, v74
	v_pk_fma_f32 v[78:79], v[72:73], s[66:67], v[76:77] op_sel_hi:[1,0,0]
	v_mul_f32_e32 v75, 0xbf38aa3b, v75
	s_mov_b32 s92, 0x3f35f0e3
	v_exp_f32_e32 v74, v74
	v_exp_f32_e32 v75, v75
	v_pk_fma_f32 v[78:79], v[72:73], v[78:79], s[92:93] op_sel_hi:[1,1,0]
	s_nop 0
	v_pk_fma_f32 v[78:79], v[72:73], v[78:79], s[28:29] op_sel_hi:[1,1,0]
	s_nop 0
	v_pk_fma_f32 v[78:79], v[72:73], v[78:79], s[76:77] op_sel_hi:[1,1,0]
	v_cmp_gt_f32_e32 vcc, 0, v65
	v_pk_mul_f32 v[72:73], v[72:73], v[78:79]
	s_nop 0
	v_pk_mul_f32 v[72:73], v[74:75], v[72:73]
	s_nop 0
	v_pk_mul_f32 v[74:75], v[64:65], v[72:73]
	v_pk_fma_f32 v[72:73], v[64:65], v[72:73], v[64:65] neg_lo:[1,0,0] neg_hi:[1,0,0]
	s_nop 0
	v_cndmask_b32_e32 v65, v73, v75, vcc
	v_cmp_gt_f32_e32 vcc, 0, v64
	s_nop 1
	v_cndmask_b32_e32 v64, v72, v74, vcc
	v_pk_mul_f32 v[64:65], v[68:69], v[64:65]
	v_cmp_gt_f32_e32 vcc, 0, v67
	v_cvt_pk_bf16_f32 v64, v64, v65
	v_fma_f32 v65, |v66|, s74, 1.0
	v_rcp_f32_e32 v68, v65
	v_fma_f32 v65, |v67|, s74, 1.0
	v_rcp_f32_e32 v69, v65
	v_mul_f32_e32 v65, v66, v66
	v_mul_f32_e32 v65, 0xbf38aa3b, v65
	v_exp_f32_e32 v72, v65
	v_mul_f32_e32 v65, v67, v67
	v_pk_fma_f32 v[74:75], v[68:69], s[66:67], v[76:77] op_sel_hi:[1,0,0]
	v_mul_f32_e32 v65, 0xbf38aa3b, v65
	v_exp_f32_e32 v73, v65
	v_pk_fma_f32 v[74:75], v[68:69], v[74:75], s[92:93] op_sel_hi:[1,1,0]
	s_movk_i32 s66, 0x1600
	v_pk_fma_f32 v[74:75], v[68:69], v[74:75], s[28:29] op_sel_hi:[1,1,0]
	s_nop 0
	v_pk_fma_f32 v[74:75], v[68:69], v[74:75], s[76:77] op_sel_hi:[1,1,0]
	s_nop 0
	v_pk_mul_f32 v[68:69], v[68:69], v[74:75]
	s_nop 0
	v_pk_mul_f32 v[68:69], v[72:73], v[68:69]
	s_nop 0
	v_pk_mul_f32 v[72:73], v[66:67], v[68:69]
	v_pk_fma_f32 v[68:69], v[66:67], v[68:69], v[66:67] neg_lo:[1,0,0] neg_hi:[1,0,0]
	s_nop 0
	v_cndmask_b32_e32 v67, v69, v73, vcc
	v_cmp_gt_f32_e32 vcc, 0, v66
	s_nop 1
	v_cndmask_b32_e32 v66, v68, v72, vcc
	v_pk_mul_f32 v[66:67], v[70:71], v[66:67]
	s_nop 0
	v_cvt_pk_bf16_f32 v65, v66, v67
	v_mov_b64_e32 v[66:67], s[26:27]
	v_mad_i64_i32 v[66:67], s[92:93], v146, s66, v[66:67]
	v_lshl_add_u64 v[66:67], v[152:153], 1, v[66:67]
	global_store_dwordx2 v[66:67], v[64:65], off

.LBB0_799:
	v_readlane_b32 s8, v242, 27
	v_cmp_gt_i32_e32 vcc, s35, v134
	v_readlane_b32 s9, v242, 28
	s_add_i32 s66, s22, 48
	s_and_b64 s[92:93], s[8:9], vcc
	v_add_u32_e32 v124, s94, v134
	s_and_saveexec_b64 s[94:95], s[92:93]
	s_cbranch_execz .LBB0_801
	s_cmp_lt_i32 s66, s35
	s_cselect_b64 vcc, -1, 0
	s_cmp_ge_i32 s66, s24
	s_cselect_b64 s[70:71], -1, 0
	v_pk_fma_f32 v[68:69], v[88:89], v[114:115], v[68:69]
	s_and_b64 s[70:71], vcc, s[70:71]
	v_pk_fma_f32 v[70:71], v[90:91], v[132:133], v[70:71]
	v_pk_add_f32 v[68:69], v[92:93], v[68:69]
	v_pk_fma_f32 v[64:65], v[80:81], v[106:107], v[64:65]
	v_pk_add_f32 v[70:71], v[94:95], v[70:71]
	v_pk_fma_f32 v[66:67], v[82:83], v[112:113], v[66:67]
	v_pk_add_f32 v[64:65], v[84:85], v[64:65]
	v_pk_add_f32 v[66:67], v[86:87], v[66:67]
	s_mov_b32 s28, 0x3f35f0e3
	s_mov_b32 s76, 0xbe11a98e
	s_mov_b32 s8, 0x3e027906
	s_cmp_eq_u64 s[70:71], 0
	s_cbranch_scc1 .Lffe_801
	v_cmp_eq_u32_e32 vcc, s37, v134
	v_pk_fma_f32 v[74:75], v[88:89], v[114:115], v[68:69] neg_lo:[1,0,0] neg_hi:[1,0,0]
	s_nop 0
	s_and_b64 vcc, s[70:71], vcc
	v_pk_fma_f32 v[72:73], v[158:159], v[132:133], v[70:71]
	v_cndmask_b32_e32 v69, v69, v75, vcc
	v_cndmask_b32_e32 v68, v68, v74, vcc
	v_pk_fma_f32 v[74:75], v[80:81], v[106:107], v[64:65] neg_lo:[1,0,0] neg_hi:[1,0,0]
	v_cndmask_b32_e32 v71, v71, v73, vcc
	v_cndmask_b32_e32 v70, v70, v72, vcc
	v_pk_fma_f32 v[72:73], v[156:157], v[112:113], v[66:67]
	v_cndmask_b32_e32 v65, v65, v75, vcc
	v_cndmask_b32_e32 v64, v64, v74, vcc
	v_cndmask_b32_e32 v67, v67, v73, vcc
	v_cndmask_b32_e32 v66, v66, v72, vcc
.Lffe_801:
	v_fma_f32 v72, |v64|, s74, 1.0
	v_fma_f32 v73, |v65|, s74, 1.0
	v_rcp_f32_e32 v72, v72
	v_rcp_f32_e32 v73, v73
	s_mov_b32 s70, 0xbf3a00e3
	v_mul_f32_e32 v74, v64, v64
	v_mov_b64_e32 v[76:77], s[70:71]
	s_mov_b32 s70, 0x3f07dc22
	v_mul_f32_e32 v75, v65, v65
	v_mul_f32_e32 v74, 0xbf38aa3b, v74
	v_pk_fma_f32 v[78:79], v[72:73], s[70:71], v[76:77] op_sel_hi:[1,0,0]
	v_mul_f32_e32 v75, 0xbf38aa3b, v75
	v_exp_f32_e32 v74, v74
	v_exp_f32_e32 v75, v75
	v_pk_fma_f32 v[78:79], v[72:73], v[78:79], s[28:29] op_sel_hi:[1,1,0]
	s_nop 0
	v_pk_fma_f32 v[78:79], v[72:73], v[78:79], s[76:77] op_sel_hi:[1,1,0]
	s_nop 0
	v_pk_fma_f32 v[78:79], v[72:73], v[78:79], s[8:9] op_sel_hi:[1,1,0]
	v_cmp_gt_f32_e32 vcc, 0, v65
	v_pk_mul_f32 v[72:73], v[72:73], v[78:79]
	s_nop 0
	v_pk_mul_f32 v[72:73], v[74:75], v[72:73]
	s_nop 0
	v_pk_mul_f32 v[74:75], v[64:65], v[72:73]
	v_pk_fma_f32 v[72:73], v[64:65], v[72:73], v[64:65] neg_lo:[1,0,0] neg_hi:[1,0,0]
	s_nop 0
	v_cndmask_b32_e32 v65, v73, v75, vcc
	v_cmp_gt_f32_e32 vcc, 0, v64
	s_nop 1
	v_cndmask_b32_e32 v64, v72, v74, vcc
	v_pk_mul_f32 v[64:65], v[68:69], v[64:65]
	v_cmp_gt_f32_e32 vcc, 0, v67
	v_cvt_pk_bf16_f32 v64, v64, v65
	v_fma_f32 v65, |v66|, s74, 1.0
	v_rcp_f32_e32 v68, v65
	v_fma_f32 v65, |v67|, s74, 1.0
	v_rcp_f32_e32 v69, v65
	v_mul_f32_e32 v65, v66, v66
	v_mul_f32_e32 v65, 0xbf38aa3b, v65
	v_exp_f32_e32 v72, v65
	v_mul_f32_e32 v65, v67, v67
	v_pk_fma_f32 v[74:75], v[68:69], s[70:71], v[76:77] op_sel_hi:[1,0,0]
	v_mul_f32_e32 v65, 0xbf38aa3b, v65
	v_exp_f32_e32 v73, v65
	v_pk_fma_f32 v[74:75], v[68:69], v[74:75], s[28:29] op_sel_hi:[1,1,0]
	s_movk_i32 s70, 0x1600
	v_pk_fma_f32 v[74:75], v[68:69], v[74:75], s[76:77] op_sel_hi:[1,1,0]
	s_nop 0
	v_pk_fma_f32 v[74:75], v[68:69], v[74:75], s[8:9] op_sel_hi:[1,1,0]
	s_nop 0
	v_pk_mul_f32 v[68:69], v[68:69], v[74:75]
	s_nop 0
	v_pk_mul_f32 v[68:69], v[72:73], v[68:69]
	s_nop 0
	v_pk_mul_f32 v[72:73], v[66:67], v[68:69]
	v_pk_fma_f32 v[68:69], v[66:67], v[68:69], v[66:67] neg_lo:[1,0,0] neg_hi:[1,0,0]
	s_nop 0
	v_cndmask_b32_e32 v67, v69, v73, vcc
	v_cmp_gt_f32_e32 vcc, 0, v66
	s_nop 1
	v_cndmask_b32_e32 v66, v68, v72, vcc
	v_pk_mul_f32 v[66:67], v[70:71], v[66:67]
	s_nop 0
	v_cvt_pk_bf16_f32 v65, v66, v67
	v_mov_b64_e32 v[66:67], s[26:27]
	v_mad_i64_i32 v[66:67], s[70:71], v124, s70, v[66:67]
	v_readlane_b32 s70, v242, 0
	v_readlane_b32 s71, v242, 1
	v_lshl_add_u64 v[66:67], v[152:153], 1, v[66:67]
	global_store_dwordx2 v[66:67], v[64:65], off

.LBB0_805:
	v_xor_b32_e32 v59, 0x80000000, v75
	v_xor_b32_e32 v58, 0x80000000, v74
	v_xor_b32_e32 v57, 0x80000000, v67
	v_xor_b32_e32 v56, 0x80000000, v66
	s_and_saveexec_b64 s[48:49], s[50:51]
	s_cbranch_execz .LBB0_807
	s_cmp_ge_i32 s25, s24
	v_pk_fma_f32 v[52:53], v[72:73], v[120:121], v[52:53]
	s_cselect_b64 s[50:51], -1, 0
	v_pk_fma_f32 v[54:55], v[74:75], v[122:123], v[54:55]
	v_pk_add_f32 v[52:53], v[76:77], v[52:53]
	v_pk_fma_f32 v[48:49], v[64:65], v[108:109], v[48:49]
	v_pk_add_f32 v[54:55], v[78:79], v[54:55]
	v_pk_fma_f32 v[50:51], v[66:67], v[110:111], v[50:51]
	v_pk_add_f32 v[48:49], v[68:69], v[48:49]
	v_pk_add_f32 v[50:51], v[70:71], v[50:51]
	s_mov_b32 s28, 0x3f35f0e3
	s_mov_b32 s76, 0xbe11a98e
	s_mov_b32 s8, 0x3e027906
	s_cmp_eq_u64 s[50:51], 0
	s_cbranch_scc1 .Lffe_807
	v_cmp_eq_u32_e32 vcc, s37, v229
	v_pk_fma_f32 v[62:63], v[72:73], v[120:121], v[52:53] neg_lo:[1,0,0] neg_hi:[1,0,0]
	s_nop 0
	s_and_b64 vcc, s[50:51], vcc
	v_pk_fma_f32 v[60:61], v[58:59], v[122:123], v[54:55]
	v_cndmask_b32_e32 v53, v53, v63, vcc
	v_cndmask_b32_e32 v52, v52, v62, vcc
	v_pk_fma_f32 v[62:63], v[64:65], v[108:109], v[48:49] neg_lo:[1,0,0] neg_hi:[1,0,0]
	v_cndmask_b32_e32 v55, v55, v61, vcc
	v_cndmask_b32_e32 v54, v54, v60, vcc
	v_pk_fma_f32 v[60:61], v[56:57], v[110:111], v[50:51]
	v_cndmask_b32_e32 v49, v49, v63, vcc
	v_cndmask_b32_e32 v48, v48, v62, vcc
	v_cndmask_b32_e32 v51, v51, v61, vcc
	v_cndmask_b32_e32 v50, v50, v60, vcc
.Lffe_807:
	v_fma_f32 v60, |v48|, s74, 1.0
	v_fma_f32 v61, |v49|, s74, 1.0
	v_rcp_f32_e32 v60, v60
	v_rcp_f32_e32 v61, v61
	s_mov_b32 s50, 0xbf3a00e3
	v_mul_f32_e32 v62, v48, v48
	v_mov_b64_e32 v[108:109], s[50:51]
	s_mov_b32 s50, 0x3f07dc22
	v_mul_f32_e32 v63, v49, v49
	v_mul_f32_e32 v62, 0xbf38aa3b, v62
	v_pk_fma_f32 v[110:111], v[60:61], s[50:51], v[108:109] op_sel_hi:[1,0,0]
	v_mul_f32_e32 v63, 0xbf38aa3b, v63
	v_exp_f32_e32 v62, v62
	v_exp_f32_e32 v63, v63
	v_pk_fma_f32 v[110:111], v[60:61], v[110:111], s[28:29] op_sel_hi:[1,1,0]
	s_nop 0
	v_pk_fma_f32 v[110:111], v[60:61], v[110:111], s[76:77] op_sel_hi:[1,1,0]
	s_nop 0
	v_pk_fma_f32 v[110:111], v[60:61], v[110:111], s[8:9] op_sel_hi:[1,1,0]
	v_cmp_gt_f32_e32 vcc, 0, v49
	v_pk_mul_f32 v[60:61], v[60:61], v[110:111]
	s_nop 0
	v_pk_mul_f32 v[60:61], v[62:63], v[60:61]
	s_nop 0
	v_pk_mul_f32 v[62:63], v[48:49], v[60:61]
	v_pk_fma_f32 v[60:61], v[48:49], v[60:61], v[48:49] neg_lo:[1,0,0] neg_hi:[1,0,0]
	s_nop 0
	v_cndmask_b32_e32 v49, v61, v63, vcc
	v_cmp_gt_f32_e32 vcc, 0, v48
	s_nop 1
	v_cndmask_b32_e32 v48, v60, v62, vcc
	v_pk_mul_f32 v[48:49], v[52:53], v[48:49]
	v_cmp_gt_f32_e32 vcc, 0, v51
	v_cvt_pk_bf16_f32 v48, v48, v49
	v_fma_f32 v49, |v50|, s74, 1.0
	v_rcp_f32_e32 v52, v49
	v_fma_f32 v49, |v51|, s74, 1.0
	v_rcp_f32_e32 v53, v49
	v_mul_f32_e32 v49, v50, v50
	v_mul_f32_e32 v49, 0xbf38aa3b, v49
	v_exp_f32_e32 v60, v49
	v_mul_f32_e32 v49, v51, v51
	v_pk_fma_f32 v[62:63], v[52:53], s[50:51], v[108:109] op_sel_hi:[1,0,0]
	v_mul_f32_e32 v49, 0xbf38aa3b, v49
	v_exp_f32_e32 v61, v49
	v_pk_fma_f32 v[62:63], v[52:53], v[62:63], s[28:29] op_sel_hi:[1,1,0]
	s_movk_i32 s50, 0x1600
	v_pk_fma_f32 v[62:63], v[52:53], v[62:63], s[76:77] op_sel_hi:[1,1,0]
	s_nop 0
	v_pk_fma_f32 v[62:63], v[52:53], v[62:63], s[8:9] op_sel_hi:[1,1,0]
	s_nop 0
	v_pk_mul_f32 v[52:53], v[52:53], v[62:63]
	s_nop 0
	v_pk_mul_f32 v[52:53], v[60:61], v[52:53]
	s_nop 0
	v_pk_mul_f32 v[60:61], v[50:51], v[52:53]
	v_pk_fma_f32 v[52:53], v[50:51], v[52:53], v[50:51] neg_lo:[1,0,0] neg_hi:[1,0,0]
	s_nop 0
	v_cndmask_b32_e32 v51, v53, v61, vcc
	v_cmp_gt_f32_e32 vcc, 0, v50
	s_nop 1
	v_cndmask_b32_e32 v50, v52, v60, vcc
	v_pk_mul_f32 v[50:51], v[54:55], v[50:51]
	s_nop 0
	v_cvt_pk_bf16_f32 v49, v50, v51
	v_mov_b64_e32 v[50:51], s[26:27]
	v_mad_i64_i32 v[50:51], s[50:51], v155, s50, v[50:51]
	v_lshl_add_u64 v[50:51], v[152:153], 1, v[50:51]
	global_store_dwordx2 v[50:51], v[48:49], off offset:8

.LBB0_811:
	s_and_saveexec_b64 s[48:49], s[12:13]
	s_cbranch_execz .LBB0_813
	s_cmp_lt_i32 s23, s35
	s_cselect_b64 s[12:13], -1, 0
	s_cmp_ge_i32 s23, s24
	s_cselect_b64 s[50:51], -1, 0
	v_pk_fma_f32 v[44:45], v[72:73], v[116:117], v[44:45]
	s_and_b64 s[12:13], s[12:13], s[50:51]
	v_pk_fma_f32 v[46:47], v[74:75], v[118:119], v[46:47]
	v_pk_add_f32 v[44:45], v[76:77], v[44:45]
	v_pk_fma_f32 v[40:41], v[64:65], v[112:113], v[40:41]
	v_pk_add_f32 v[46:47], v[78:79], v[46:47]
	v_pk_fma_f32 v[42:43], v[66:67], v[114:115], v[42:43]
	v_pk_add_f32 v[40:41], v[68:69], v[40:41]
	v_pk_add_f32 v[42:43], v[70:71], v[42:43]
	s_mov_b32 s28, 0x3f35f0e3
	s_mov_b32 s50, 0xbe11a98e
	s_mov_b32 s8, 0x3e027906
	s_cmp_eq_u64 s[12:13], 0
	s_cbranch_scc1 .Lffe_813
	v_cmp_eq_u32_e32 vcc, s37, v228
	v_pk_fma_f32 v[50:51], v[72:73], v[116:117], v[44:45] neg_lo:[1,0,0] neg_hi:[1,0,0]
	s_nop 0
	s_and_b64 vcc, s[12:13], vcc
	v_pk_fma_f32 v[48:49], v[58:59], v[118:119], v[46:47]
	v_cndmask_b32_e32 v45, v45, v51, vcc
	v_cndmask_b32_e32 v44, v44, v50, vcc
	v_pk_fma_f32 v[50:51], v[64:65], v[112:113], v[40:41] neg_lo:[1,0,0] neg_hi:[1,0,0]
	v_cndmask_b32_e32 v47, v47, v49, vcc
	v_cndmask_b32_e32 v46, v46, v48, vcc
	v_pk_fma_f32 v[48:49], v[56:57], v[114:115], v[42:43]
	v_cndmask_b32_e32 v41, v41, v51, vcc
	v_cndmask_b32_e32 v40, v40, v50, vcc
	v_cndmask_b32_e32 v43, v43, v49, vcc
	v_cndmask_b32_e32 v42, v42, v48, vcc
.Lffe_813:
	v_fma_f32 v48, |v40|, s74, 1.0
	v_fma_f32 v49, |v41|, s74, 1.0
	v_rcp_f32_e32 v48, v48
	v_rcp_f32_e32 v49, v49
	s_mov_b32 s12, 0xbf3a00e3
	v_mul_f32_e32 v50, v40, v40
	v_mov_b64_e32 v[52:53], s[12:13]
	s_mov_b32 s12, 0x3f07dc22
	v_mul_f32_e32 v51, v41, v41
	v_mul_f32_e32 v50, 0xbf38aa3b, v50
	v_pk_fma_f32 v[54:55], v[48:49], s[12:13], v[52:53] op_sel_hi:[1,0,0]
	v_mul_f32_e32 v51, 0xbf38aa3b, v51
	v_exp_f32_e32 v50, v50
	v_exp_f32_e32 v51, v51
	v_pk_fma_f32 v[54:55], v[48:49], v[54:55], s[28:29] op_sel_hi:[1,1,0]
	s_nop 0
	v_pk_fma_f32 v[54:55], v[48:49], v[54:55], s[50:51] op_sel_hi:[1,1,0]
	s_nop 0
	v_pk_fma_f32 v[54:55], v[48:49], v[54:55], s[8:9] op_sel_hi:[1,1,0]
	v_cmp_gt_f32_e32 vcc, 0, v41
	v_pk_mul_f32 v[48:49], v[48:49], v[54:55]
	s_nop 0
	v_pk_mul_f32 v[48:49], v[50:51], v[48:49]
	s_nop 0
	v_pk_mul_f32 v[50:51], v[40:41], v[48:49]
	v_pk_fma_f32 v[48:49], v[40:41], v[48:49], v[40:41] neg_lo:[1,0,0] neg_hi:[1,0,0]
	s_nop 0
	v_cndmask_b32_e32 v41, v49, v51, vcc
	v_cmp_gt_f32_e32 vcc, 0, v40
	s_nop 1
	v_cndmask_b32_e32 v40, v48, v50, vcc
	v_pk_mul_f32 v[40:41], v[44:45], v[40:41]
	v_cmp_gt_f32_e32 vcc, 0, v43
	v_cvt_pk_bf16_f32 v40, v40, v41
	v_fma_f32 v41, |v42|, s74, 1.0
	v_rcp_f32_e32 v44, v41
	v_fma_f32 v41, |v43|, s74, 1.0
	v_rcp_f32_e32 v45, v41
	v_mul_f32_e32 v41, v42, v42
	v_mul_f32_e32 v41, 0xbf38aa3b, v41
	v_exp_f32_e32 v48, v41
	v_mul_f32_e32 v41, v43, v43
	v_pk_fma_f32 v[50:51], v[44:45], s[12:13], v[52:53] op_sel_hi:[1,0,0]
	v_mul_f32_e32 v41, 0xbf38aa3b, v41
	v_exp_f32_e32 v49, v41
	v_pk_fma_f32 v[50:51], v[44:45], v[50:51], s[28:29] op_sel_hi:[1,1,0]
	s_movk_i32 s12, 0x1600
	v_pk_fma_f32 v[50:51], v[44:45], v[50:51], s[50:51] op_sel_hi:[1,1,0]
	s_nop 0
	v_pk_fma_f32 v[50:51], v[44:45], v[50:51], s[8:9] op_sel_hi:[1,1,0]
	s_nop 0
	v_pk_mul_f32 v[44:45], v[44:45], v[50:51]
	s_nop 0
	v_pk_mul_f32 v[44:45], v[48:49], v[44:45]
	s_nop 0
	v_pk_mul_f32 v[48:49], v[42:43], v[44:45]
	v_pk_fma_f32 v[44:45], v[42:43], v[44:45], v[42:43] neg_lo:[1,0,0] neg_hi:[1,0,0]
	s_nop 0
	v_cndmask_b32_e32 v43, v45, v49, vcc
	v_cmp_gt_f32_e32 vcc, 0, v42
	s_nop 1
	v_cndmask_b32_e32 v42, v44, v48, vcc
	v_pk_mul_f32 v[42:43], v[46:47], v[42:43]
	s_nop 0
	v_cvt_pk_bf16_f32 v41, v42, v43
	v_mov_b64_e32 v[42:43], s[26:27]
	v_mad_i64_i32 v[42:43], s[12:13], v145, s12, v[42:43]
	v_lshl_add_u64 v[42:43], v[152:153], 1, v[42:43]
	global_store_dwordx2 v[42:43], v[40:41], off offset:8

.LBB0_817:
	s_and_saveexec_b64 s[12:13], s[14:15]
	s_cbranch_execz .LBB0_819
	s_cmp_lt_i32 s67, s35
	s_cselect_b64 s[14:15], -1, 0
	s_cmp_ge_i32 s67, s24
	s_cselect_b64 s[48:49], -1, 0
	v_pk_fma_f32 v[36:37], v[72:73], v[102:103], v[36:37]
	s_and_b64 s[14:15], s[14:15], s[48:49]
	v_pk_fma_f32 v[38:39], v[74:75], v[106:107], v[38:39]
	v_pk_add_f32 v[36:37], v[76:77], v[36:37]
	v_pk_fma_f32 v[32:33], v[64:65], v[98:99], v[32:33]
	v_pk_add_f32 v[38:39], v[78:79], v[38:39]
	v_pk_fma_f32 v[34:35], v[66:67], v[100:101], v[34:35]
	v_pk_add_f32 v[32:33], v[68:69], v[32:33]
	v_pk_add_f32 v[34:35], v[70:71], v[34:35]
	s_mov_b32 s28, 0x3f35f0e3
	s_mov_b32 s48, 0xbe11a98e
	s_mov_b32 s8, 0x3e027906
	s_cmp_eq_u64 s[14:15], 0
	s_cbranch_scc1 .Lffe_819
	v_cmp_eq_u32_e32 vcc, s37, v211
	v_pk_fma_f32 v[42:43], v[72:73], v[102:103], v[36:37] neg_lo:[1,0,0] neg_hi:[1,0,0]
	s_nop 0
	s_and_b64 vcc, s[14:15], vcc
	v_pk_fma_f32 v[40:41], v[58:59], v[106:107], v[38:39]
	v_cndmask_b32_e32 v37, v37, v43, vcc
	v_cndmask_b32_e32 v36, v36, v42, vcc
	v_pk_fma_f32 v[42:43], v[64:65], v[98:99], v[32:33] neg_lo:[1,0,0] neg_hi:[1,0,0]
	v_cndmask_b32_e32 v39, v39, v41, vcc
	v_cndmask_b32_e32 v38, v38, v40, vcc
	v_pk_fma_f32 v[40:41], v[56:57], v[100:101], v[34:35]
	v_cndmask_b32_e32 v33, v33, v43, vcc
	v_cndmask_b32_e32 v32, v32, v42, vcc
	v_cndmask_b32_e32 v35, v35, v41, vcc
	v_cndmask_b32_e32 v34, v34, v40, vcc
.Lffe_819:
	v_fma_f32 v40, |v32|, s74, 1.0
	v_fma_f32 v41, |v33|, s74, 1.0
	v_rcp_f32_e32 v40, v40
	v_rcp_f32_e32 v41, v41
	s_mov_b32 s14, 0xbf3a00e3
	v_mul_f32_e32 v42, v32, v32
	v_mov_b64_e32 v[44:45], s[14:15]
	s_mov_b32 s14, 0x3f07dc22
	v_mul_f32_e32 v43, v33, v33
	v_mul_f32_e32 v42, 0xbf38aa3b, v42
	v_pk_fma_f32 v[46:47], v[40:41], s[14:15], v[44:45] op_sel_hi:[1,0,0]
	v_mul_f32_e32 v43, 0xbf38aa3b, v43
	v_exp_f32_e32 v42, v42
	v_exp_f32_e32 v43, v43
	v_pk_fma_f32 v[46:47], v[40:41], v[46:47], s[28:29] op_sel_hi:[1,1,0]
	s_nop 0
	v_pk_fma_f32 v[46:47], v[40:41], v[46:47], s[48:49] op_sel_hi:[1,1,0]
	s_nop 0
	v_pk_fma_f32 v[46:47], v[40:41], v[46:47], s[8:9] op_sel_hi:[1,1,0]
	v_cmp_gt_f32_e32 vcc, 0, v33
	v_pk_mul_f32 v[40:41], v[40:41], v[46:47]
	s_nop 0
	v_pk_mul_f32 v[40:41], v[42:43], v[40:41]
	s_nop 0
	v_pk_mul_f32 v[42:43], v[32:33], v[40:41]
	v_pk_fma_f32 v[40:41], v[32:33], v[40:41], v[32:33] neg_lo:[1,0,0] neg_hi:[1,0,0]
	s_nop 0
	v_cndmask_b32_e32 v33, v41, v43, vcc
	v_cmp_gt_f32_e32 vcc, 0, v32
	s_nop 1
	v_cndmask_b32_e32 v32, v40, v42, vcc
	v_pk_mul_f32 v[32:33], v[36:37], v[32:33]
	v_cmp_gt_f32_e32 vcc, 0, v35
	v_cvt_pk_bf16_f32 v32, v32, v33
	v_fma_f32 v33, |v34|, s74, 1.0
	v_rcp_f32_e32 v36, v33
	v_fma_f32 v33, |v35|, s74, 1.0
	v_rcp_f32_e32 v37, v33
	v_mul_f32_e32 v33, v34, v34
	v_mul_f32_e32 v33, 0xbf38aa3b, v33
	v_exp_f32_e32 v40, v33
	v_mul_f32_e32 v33, v35, v35
	v_pk_fma_f32 v[42:43], v[36:37], s[14:15], v[44:45] op_sel_hi:[1,0,0]
	v_mul_f32_e32 v33, 0xbf38aa3b, v33
	v_exp_f32_e32 v41, v33
	v_pk_fma_f32 v[42:43], v[36:37], v[42:43], s[28:29] op_sel_hi:[1,1,0]
	s_movk_i32 s14, 0x1600
	v_pk_fma_f32 v[42:43], v[36:37], v[42:43], s[48:49] op_sel_hi:[1,1,0]
	s_nop 0
	v_pk_fma_f32 v[42:43], v[36:37], v[42:43], s[8:9] op_sel_hi:[1,1,0]
	s_nop 0
	v_pk_mul_f32 v[36:37], v[36:37], v[42:43]
	s_nop 0
	v_pk_mul_f32 v[36:37], v[40:41], v[36:37]
	s_nop 0
	v_pk_mul_f32 v[40:41], v[34:35], v[36:37]
	v_pk_fma_f32 v[36:37], v[34:35], v[36:37], v[34:35] neg_lo:[1,0,0] neg_hi:[1,0,0]
	s_nop 0
	v_cndmask_b32_e32 v35, v37, v41, vcc
	v_cmp_gt_f32_e32 vcc, 0, v34
	s_nop 1
	v_cndmask_b32_e32 v34, v36, v40, vcc
	v_pk_mul_f32 v[34:35], v[38:39], v[34:35]
	s_nop 0
	v_cvt_pk_bf16_f32 v33, v34, v35
	v_mov_b64_e32 v[34:35], s[26:27]
	v_mad_i64_i32 v[34:35], s[14:15], v210, s14, v[34:35]
	v_lshl_add_u64 v[34:35], v[152:153], 1, v[34:35]
	global_store_dwordx2 v[34:35], v[32:33], off offset:8

.LBB0_823:
	s_and_saveexec_b64 s[12:13], s[80:81]
	s_cbranch_execz .LBB0_825
	s_cmp_lt_i32 s69, s35
	s_cselect_b64 s[14:15], -1, 0
	s_cmp_ge_i32 s69, s24
	s_cselect_b64 s[48:49], -1, 0
	v_pk_fma_f32 v[36:37], v[72:73], v[98:99], v[36:37]
	s_and_b64 s[14:15], s[14:15], s[48:49]
	v_pk_fma_f32 v[38:39], v[74:75], v[100:101], v[38:39]
	v_pk_add_f32 v[36:37], v[76:77], v[36:37]
	v_pk_fma_f32 v[32:33], v[64:65], v[60:61], v[32:33]
	v_pk_add_f32 v[38:39], v[78:79], v[38:39]
	v_pk_fma_f32 v[34:35], v[66:67], v[62:63], v[34:35]
	v_pk_add_f32 v[32:33], v[68:69], v[32:33]
	v_pk_add_f32 v[34:35], v[70:71], v[34:35]
	s_mov_b32 s28, 0x3f35f0e3
	s_mov_b32 s48, 0xbe11a98e
	s_mov_b32 s8, 0x3e027906
	s_cmp_eq_u64 s[14:15], 0
	s_cbranch_scc1 .Lffe_825
	v_cmp_eq_u32_e32 vcc, s37, v212
	v_pk_fma_f32 v[42:43], v[72:73], v[98:99], v[36:37] neg_lo:[1,0,0] neg_hi:[1,0,0]
	s_nop 0
	s_and_b64 vcc, s[14:15], vcc
	v_pk_fma_f32 v[40:41], v[58:59], v[100:101], v[38:39]
	v_cndmask_b32_e32 v37, v37, v43, vcc
	v_cndmask_b32_e32 v36, v36, v42, vcc
	v_pk_fma_f32 v[42:43], v[64:65], v[60:61], v[32:33] neg_lo:[1,0,0] neg_hi:[1,0,0]
	v_cndmask_b32_e32 v39, v39, v41, vcc
	v_cndmask_b32_e32 v38, v38, v40, vcc
	v_pk_fma_f32 v[40:41], v[56:57], v[62:63], v[34:35]
	v_cndmask_b32_e32 v33, v33, v43, vcc
	v_cndmask_b32_e32 v32, v32, v42, vcc
	v_cndmask_b32_e32 v35, v35, v41, vcc
	v_cndmask_b32_e32 v34, v34, v40, vcc
.Lffe_825:
	v_fma_f32 v40, |v32|, s74, 1.0
	v_fma_f32 v41, |v33|, s74, 1.0
	v_rcp_f32_e32 v40, v40
	v_rcp_f32_e32 v41, v41
	s_mov_b32 s14, 0xbf3a00e3
	v_mul_f32_e32 v42, v32, v32
	v_mov_b64_e32 v[44:45], s[14:15]
	s_mov_b32 s14, 0x3f07dc22
	v_mul_f32_e32 v43, v33, v33
	v_mul_f32_e32 v42, 0xbf38aa3b, v42
	v_pk_fma_f32 v[46:47], v[40:41], s[14:15], v[44:45] op_sel_hi:[1,0,0]
	v_mul_f32_e32 v43, 0xbf38aa3b, v43
	v_exp_f32_e32 v42, v42
	v_exp_f32_e32 v43, v43
	v_pk_fma_f32 v[46:47], v[40:41], v[46:47], s[28:29] op_sel_hi:[1,1,0]
	s_nop 0
	v_pk_fma_f32 v[46:47], v[40:41], v[46:47], s[48:49] op_sel_hi:[1,1,0]
	s_nop 0
	v_pk_fma_f32 v[46:47], v[40:41], v[46:47], s[8:9] op_sel_hi:[1,1,0]
	v_cmp_gt_f32_e32 vcc, 0, v33
	v_pk_mul_f32 v[40:41], v[40:41], v[46:47]
	s_nop 0
	v_pk_mul_f32 v[40:41], v[42:43], v[40:41]
	s_nop 0
	v_pk_mul_f32 v[42:43], v[32:33], v[40:41]
	v_pk_fma_f32 v[40:41], v[32:33], v[40:41], v[32:33] neg_lo:[1,0,0] neg_hi:[1,0,0]
	s_nop 0
	v_cndmask_b32_e32 v33, v41, v43, vcc
	v_cmp_gt_f32_e32 vcc, 0, v32
	s_nop 1
	v_cndmask_b32_e32 v32, v40, v42, vcc
	v_pk_mul_f32 v[32:33], v[36:37], v[32:33]
	v_cmp_gt_f32_e32 vcc, 0, v35
	v_cvt_pk_bf16_f32 v32, v32, v33
	v_fma_f32 v33, |v34|, s74, 1.0
	v_rcp_f32_e32 v36, v33
	v_fma_f32 v33, |v35|, s74, 1.0
	v_rcp_f32_e32 v37, v33
	v_mul_f32_e32 v33, v34, v34
	v_mul_f32_e32 v33, 0xbf38aa3b, v33
	v_exp_f32_e32 v40, v33
	v_mul_f32_e32 v33, v35, v35
	v_pk_fma_f32 v[42:43], v[36:37], s[14:15], v[44:45] op_sel_hi:[1,0,0]
	v_mul_f32_e32 v33, 0xbf38aa3b, v33
	v_exp_f32_e32 v41, v33
	v_pk_fma_f32 v[42:43], v[36:37], v[42:43], s[28:29] op_sel_hi:[1,1,0]
	s_movk_i32 s14, 0x1600
	v_pk_fma_f32 v[42:43], v[36:37], v[42:43], s[48:49] op_sel_hi:[1,1,0]
	s_nop 0
	v_pk_fma_f32 v[42:43], v[36:37], v[42:43], s[8:9] op_sel_hi:[1,1,0]
	s_nop 0
	v_pk_mul_f32 v[36:37], v[36:37], v[42:43]
	s_nop 0
	v_pk_mul_f32 v[36:37], v[40:41], v[36:37]
	s_nop 0
	v_pk_mul_f32 v[40:41], v[34:35], v[36:37]
	v_pk_fma_f32 v[36:37], v[34:35], v[36:37], v[34:35] neg_lo:[1,0,0] neg_hi:[1,0,0]
	s_nop 0
	v_cndmask_b32_e32 v35, v37, v41, vcc
	v_cmp_gt_f32_e32 vcc, 0, v34
	s_nop 1
	v_cndmask_b32_e32 v34, v36, v40, vcc
	v_pk_mul_f32 v[34:35], v[38:39], v[34:35]
	s_nop 0
	v_cvt_pk_bf16_f32 v33, v34, v35
	v_mov_b64_e32 v[34:35], s[26:27]
	v_mad_i64_i32 v[34:35], s[14:15], v200, s14, v[34:35]
	v_lshl_add_u64 v[34:35], v[152:153], 1, v[34:35]
	global_store_dwordx2 v[34:35], v[32:33], off offset:8

.LBB0_827:
	s_cmp_ge_i32 s22, s24
	v_pk_fma_f32 v[20:21], v[72:73], v[52:53], v[20:21]
	s_cselect_b64 s[14:15], -1, 0
	v_pk_fma_f32 v[22:23], v[74:75], v[54:55], v[22:23]
	v_pk_add_f32 v[20:21], v[76:77], v[20:21]
	v_pk_fma_f32 v[16:17], v[64:65], v[48:49], v[16:17]
	v_pk_add_f32 v[22:23], v[78:79], v[22:23]
	v_pk_fma_f32 v[18:19], v[66:67], v[50:51], v[18:19]
	v_pk_add_f32 v[16:17], v[68:69], v[16:17]
	v_pk_add_f32 v[18:19], v[70:71], v[18:19]
	s_mov_b32 s28, 0x3f35f0e3
	s_mov_b32 s48, 0xbe11a98e
	s_mov_b32 s8, 0x3e027906
	s_cmp_eq_u64 s[14:15], 0
	s_cbranch_scc1 .Lffe_828
	v_cmp_eq_u32_e32 vcc, s37, v198
	v_pk_fma_f32 v[26:27], v[72:73], v[52:53], v[20:21] neg_lo:[1,0,0] neg_hi:[1,0,0]
	s_nop 0
	s_and_b64 vcc, s[14:15], vcc
	v_pk_fma_f32 v[24:25], v[58:59], v[54:55], v[22:23]
	v_cndmask_b32_e32 v21, v21, v27, vcc
	v_cndmask_b32_e32 v20, v20, v26, vcc
	v_pk_fma_f32 v[26:27], v[64:65], v[48:49], v[16:17] neg_lo:[1,0,0] neg_hi:[1,0,0]
	v_cndmask_b32_e32 v23, v23, v25, vcc
	v_cndmask_b32_e32 v22, v22, v24, vcc
	v_pk_fma_f32 v[24:25], v[56:57], v[50:51], v[18:19]
	v_cndmask_b32_e32 v17, v17, v27, vcc
	v_cndmask_b32_e32 v16, v16, v26, vcc
	v_cndmask_b32_e32 v19, v19, v25, vcc
	v_cndmask_b32_e32 v18, v18, v24, vcc
.Lffe_828:
	v_fma_f32 v24, |v16|, s74, 1.0
	v_fma_f32 v25, |v17|, s74, 1.0
	v_rcp_f32_e32 v24, v24
	v_rcp_f32_e32 v25, v25
	s_mov_b32 s14, 0xbf3a00e3
	v_mul_f32_e32 v26, v16, v16
	v_mov_b64_e32 v[28:29], s[14:15]
	s_mov_b32 s14, 0x3f07dc22
	v_mul_f32_e32 v27, v17, v17
	v_mul_f32_e32 v26, 0xbf38aa3b, v26
	v_pk_fma_f32 v[30:31], v[24:25], s[14:15], v[28:29] op_sel_hi:[1,0,0]
	v_mul_f32_e32 v27, 0xbf38aa3b, v27
	v_exp_f32_e32 v26, v26
	v_exp_f32_e32 v27, v27
	v_pk_fma_f32 v[30:31], v[24:25], v[30:31], s[28:29] op_sel_hi:[1,1,0]
	s_nop 0
	v_pk_fma_f32 v[30:31], v[24:25], v[30:31], s[48:49] op_sel_hi:[1,1,0]
	s_nop 0
	v_pk_fma_f32 v[30:31], v[24:25], v[30:31], s[8:9] op_sel_hi:[1,1,0]
	v_cmp_gt_f32_e32 vcc, 0, v17
	v_pk_mul_f32 v[24:25], v[24:25], v[30:31]
	s_nop 0
	v_pk_mul_f32 v[24:25], v[26:27], v[24:25]
	s_nop 0
	v_pk_mul_f32 v[26:27], v[16:17], v[24:25]
	v_pk_fma_f32 v[24:25], v[16:17], v[24:25], v[16:17] neg_lo:[1,0,0] neg_hi:[1,0,0]
	s_nop 0
	v_cndmask_b32_e32 v17, v25, v27, vcc
	v_cmp_gt_f32_e32 vcc, 0, v16
	s_nop 1
	v_cndmask_b32_e32 v16, v24, v26, vcc
	v_pk_mul_f32 v[16:17], v[20:21], v[16:17]
	v_cmp_gt_f32_e32 vcc, 0, v19
	v_cvt_pk_bf16_f32 v16, v16, v17
	v_fma_f32 v17, |v18|, s74, 1.0
	v_rcp_f32_e32 v20, v17
	v_fma_f32 v17, |v19|, s74, 1.0
	v_rcp_f32_e32 v21, v17
	v_mul_f32_e32 v17, v18, v18
	v_mul_f32_e32 v17, 0xbf38aa3b, v17
	v_exp_f32_e32 v24, v17
	v_mul_f32_e32 v17, v19, v19
	v_pk_fma_f32 v[26:27], v[20:21], s[14:15], v[28:29] op_sel_hi:[1,0,0]
	v_mul_f32_e32 v17, 0xbf38aa3b, v17
	v_exp_f32_e32 v25, v17
	v_pk_fma_f32 v[26:27], v[20:21], v[26:27], s[28:29] op_sel_hi:[1,1,0]
	s_movk_i32 s14, 0x1600
	v_pk_fma_f32 v[26:27], v[20:21], v[26:27], s[48:49] op_sel_hi:[1,1,0]
	s_nop 0
	v_pk_fma_f32 v[26:27], v[20:21], v[26:27], s[8:9] op_sel_hi:[1,1,0]
	s_nop 0
	v_pk_mul_f32 v[20:21], v[20:21], v[26:27]
	s_nop 0
	v_pk_mul_f32 v[20:21], v[24:25], v[20:21]
	s_nop 0
	v_pk_mul_f32 v[24:25], v[18:19], v[20:21]
	v_pk_fma_f32 v[20:21], v[18:19], v[20:21], v[18:19] neg_lo:[1,0,0] neg_hi:[1,0,0]
	s_nop 0
	v_cndmask_b32_e32 v19, v21, v25, vcc
	v_cmp_gt_f32_e32 vcc, 0, v18
	s_nop 1
	v_cndmask_b32_e32 v18, v20, v24, vcc
	v_pk_mul_f32 v[18:19], v[22:23], v[18:19]
	s_nop 0
	v_cvt_pk_bf16_f32 v17, v18, v19
	v_mov_b64_e32 v[18:19], s[26:27]
	v_mad_i64_i32 v[18:19], s[14:15], v105, s14, v[18:19]
	v_lshl_add_u64 v[18:19], v[152:153], 1, v[18:19]
	global_store_dwordx2 v[18:19], v[16:17], off offset:8

.LBB0_832:
	s_and_saveexec_b64 s[12:13], s[16:17]
	s_cbranch_execz .LBB0_834
	s_cmp_lt_i32 s60, s35
	s_cselect_b64 s[14:15], -1, 0
	s_cmp_ge_i32 s60, s24
	s_cselect_b64 s[16:17], -1, 0
	v_pk_fma_f32 v[12:13], v[72:73], v[44:45], v[12:13]
	s_and_b64 s[14:15], s[14:15], s[16:17]
	v_pk_fma_f32 v[14:15], v[74:75], v[46:47], v[14:15]
	v_pk_add_f32 v[12:13], v[76:77], v[12:13]
	v_pk_fma_f32 v[8:9], v[64:65], v[40:41], v[8:9]
	v_pk_add_f32 v[14:15], v[78:79], v[14:15]
	v_pk_fma_f32 v[10:11], v[66:67], v[42:43], v[10:11]
	v_pk_add_f32 v[8:9], v[68:69], v[8:9]
	v_pk_add_f32 v[10:11], v[70:71], v[10:11]
	s_mov_b32 s16, 0x3f35f0e3
	s_mov_b32 s28, 0xbe11a98e
	s_mov_b32 s8, 0x3e027906
	s_cmp_eq_u64 s[14:15], 0
	s_cbranch_scc1 .Lffe_834
	v_cmp_eq_u32_e32 vcc, s37, v192
	v_pk_fma_f32 v[18:19], v[72:73], v[44:45], v[12:13] neg_lo:[1,0,0] neg_hi:[1,0,0]
	s_nop 0
	s_and_b64 vcc, s[14:15], vcc
	v_pk_fma_f32 v[16:17], v[58:59], v[46:47], v[14:15]
	v_cndmask_b32_e32 v13, v13, v19, vcc
	v_cndmask_b32_e32 v12, v12, v18, vcc
	v_pk_fma_f32 v[18:19], v[64:65], v[40:41], v[8:9] neg_lo:[1,0,0] neg_hi:[1,0,0]
	v_cndmask_b32_e32 v15, v15, v17, vcc
	v_cndmask_b32_e32 v14, v14, v16, vcc
	v_pk_fma_f32 v[16:17], v[56:57], v[42:43], v[10:11]
	v_cndmask_b32_e32 v9, v9, v19, vcc
	v_cndmask_b32_e32 v8, v8, v18, vcc
	v_cndmask_b32_e32 v11, v11, v17, vcc
	v_cndmask_b32_e32 v10, v10, v16, vcc
.Lffe_834:
	v_fma_f32 v16, |v8|, s74, 1.0
	v_fma_f32 v17, |v9|, s74, 1.0
	v_rcp_f32_e32 v16, v16
	v_rcp_f32_e32 v17, v17
	s_mov_b32 s14, 0xbf3a00e3
	v_mul_f32_e32 v18, v8, v8
	v_mov_b64_e32 v[20:21], s[14:15]
	s_mov_b32 s14, 0x3f07dc22
	v_mul_f32_e32 v19, v9, v9
	v_mul_f32_e32 v18, 0xbf38aa3b, v18
	v_pk_fma_f32 v[22:23], v[16:17], s[14:15], v[20:21] op_sel_hi:[1,0,0]
	v_mul_f32_e32 v19, 0xbf38aa3b, v19
	v_exp_f32_e32 v18, v18
	v_exp_f32_e32 v19, v19
	v_pk_fma_f32 v[22:23], v[16:17], v[22:23], s[16:17] op_sel_hi:[1,1,0]
	s_nop 0
	v_pk_fma_f32 v[22:23], v[16:17], v[22:23], s[28:29] op_sel_hi:[1,1,0]
	s_nop 0
	v_pk_fma_f32 v[22:23], v[16:17], v[22:23], s[8:9] op_sel_hi:[1,1,0]
	v_cmp_gt_f32_e32 vcc, 0, v9
	v_pk_mul_f32 v[16:17], v[16:17], v[22:23]
	s_nop 0
	v_pk_mul_f32 v[16:17], v[18:19], v[16:17]
	s_nop 0
	v_pk_mul_f32 v[18:19], v[8:9], v[16:17]
	v_pk_fma_f32 v[16:17], v[8:9], v[16:17], v[8:9] neg_lo:[1,0,0] neg_hi:[1,0,0]
	s_nop 0
	v_cndmask_b32_e32 v9, v17, v19, vcc
	v_cmp_gt_f32_e32 vcc, 0, v8
	s_nop 1
	v_cndmask_b32_e32 v8, v16, v18, vcc
	v_pk_mul_f32 v[8:9], v[12:13], v[8:9]
	v_cmp_gt_f32_e32 vcc, 0, v11
	v_cvt_pk_bf16_f32 v8, v8, v9
	v_fma_f32 v9, |v10|, s74, 1.0
	v_rcp_f32_e32 v12, v9
	v_fma_f32 v9, |v11|, s74, 1.0
	v_rcp_f32_e32 v13, v9
	v_mul_f32_e32 v9, v10, v10
	v_mul_f32_e32 v9, 0xbf38aa3b, v9
	v_exp_f32_e32 v16, v9
	v_mul_f32_e32 v9, v11, v11
	v_pk_fma_f32 v[18:19], v[12:13], s[14:15], v[20:21] op_sel_hi:[1,0,0]
	v_mul_f32_e32 v9, 0xbf38aa3b, v9
	v_exp_f32_e32 v17, v9
	v_pk_fma_f32 v[18:19], v[12:13], v[18:19], s[16:17] op_sel_hi:[1,1,0]
	s_movk_i32 s14, 0x1600
	v_pk_fma_f32 v[18:19], v[12:13], v[18:19], s[28:29] op_sel_hi:[1,1,0]
	s_nop 0
	v_pk_fma_f32 v[18:19], v[12:13], v[18:19], s[8:9] op_sel_hi:[1,1,0]
	s_nop 0
	v_pk_mul_f32 v[12:13], v[12:13], v[18:19]
	s_nop 0
	v_pk_mul_f32 v[12:13], v[16:17], v[12:13]
	s_nop 0
	v_pk_mul_f32 v[16:17], v[10:11], v[12:13]
	v_pk_fma_f32 v[12:13], v[10:11], v[12:13], v[10:11] neg_lo:[1,0,0] neg_hi:[1,0,0]
	s_nop 0
	v_cndmask_b32_e32 v11, v13, v17, vcc
	v_cmp_gt_f32_e32 vcc, 0, v10
	s_nop 1
	v_cndmask_b32_e32 v10, v12, v16, vcc
	v_pk_mul_f32 v[10:11], v[14:15], v[10:11]
	s_nop 0
	v_cvt_pk_bf16_f32 v9, v10, v11
	v_mov_b64_e32 v[10:11], s[26:27]
	v_mad_i64_i32 v[10:11], s[14:15], v97, s14, v[10:11]
	v_lshl_add_u64 v[10:11], v[152:153], 1, v[10:11]
	global_store_dwordx2 v[10:11], v[8:9], off offset:8

.LBB0_838:
	s_and_saveexec_b64 s[12:13], s[18:19]
	s_cbranch_execz .LBB0_840
	s_cmp_lt_i32 s64, s35
	s_cselect_b64 s[14:15], -1, 0
	s_cmp_ge_i32 s64, s24
	s_cselect_b64 s[16:17], -1, 0
	v_pk_fma_f32 v[4:5], v[72:73], v[36:37], v[4:5]
	s_and_b64 s[14:15], s[14:15], s[16:17]
	v_pk_fma_f32 v[6:7], v[74:75], v[38:39], v[6:7]
	v_pk_add_f32 v[4:5], v[76:77], v[4:5]
	v_pk_fma_f32 v[0:1], v[64:65], v[32:33], v[0:1]
	v_pk_add_f32 v[6:7], v[78:79], v[6:7]
	v_pk_fma_f32 v[2:3], v[66:67], v[34:35], v[2:3]
	v_pk_add_f32 v[0:1], v[68:69], v[0:1]
	v_pk_add_f32 v[2:3], v[70:71], v[2:3]
	s_mov_b32 s16, 0x3f35f0e3
	s_mov_b32 s18, 0xbe11a98e
	s_mov_b32 s8, 0x3e027906
	s_cmp_eq_u64 s[14:15], 0
	s_cbranch_scc1 .Lffe_840
	v_cmp_eq_u32_e32 vcc, s37, v147
	v_pk_fma_f32 v[10:11], v[72:73], v[36:37], v[4:5] neg_lo:[1,0,0] neg_hi:[1,0,0]
	s_nop 0
	s_and_b64 vcc, s[14:15], vcc
	v_pk_fma_f32 v[8:9], v[58:59], v[38:39], v[6:7]
	v_cndmask_b32_e32 v5, v5, v11, vcc
	v_cndmask_b32_e32 v4, v4, v10, vcc
	v_pk_fma_f32 v[10:11], v[64:65], v[32:33], v[0:1] neg_lo:[1,0,0] neg_hi:[1,0,0]
	v_cndmask_b32_e32 v7, v7, v9, vcc
	v_cndmask_b32_e32 v6, v6, v8, vcc
	v_pk_fma_f32 v[8:9], v[56:57], v[34:35], v[2:3]
	v_cndmask_b32_e32 v1, v1, v11, vcc
	v_cndmask_b32_e32 v0, v0, v10, vcc
	v_cndmask_b32_e32 v3, v3, v9, vcc
	v_cndmask_b32_e32 v2, v2, v8, vcc
.Lffe_840:
	v_fma_f32 v8, |v0|, s74, 1.0
	v_fma_f32 v9, |v1|, s74, 1.0
	v_rcp_f32_e32 v8, v8
	v_rcp_f32_e32 v9, v9
	s_mov_b32 s14, 0xbf3a00e3
	v_mul_f32_e32 v10, v0, v0
	v_mov_b64_e32 v[12:13], s[14:15]
	s_mov_b32 s14, 0x3f07dc22
	v_mul_f32_e32 v11, v1, v1
	v_mul_f32_e32 v10, 0xbf38aa3b, v10
	v_pk_fma_f32 v[14:15], v[8:9], s[14:15], v[12:13] op_sel_hi:[1,0,0]
	v_mul_f32_e32 v11, 0xbf38aa3b, v11
	v_exp_f32_e32 v10, v10
	v_exp_f32_e32 v11, v11
	v_pk_fma_f32 v[14:15], v[8:9], v[14:15], s[16:17] op_sel_hi:[1,1,0]
	s_nop 0
	v_pk_fma_f32 v[14:15], v[8:9], v[14:15], s[18:19] op_sel_hi:[1,1,0]
	s_nop 0
	v_pk_fma_f32 v[14:15], v[8:9], v[14:15], s[8:9] op_sel_hi:[1,1,0]
	v_cmp_gt_f32_e32 vcc, 0, v1
	v_pk_mul_f32 v[8:9], v[8:9], v[14:15]
	s_nop 0
	v_pk_mul_f32 v[8:9], v[10:11], v[8:9]
	s_nop 0
	v_pk_mul_f32 v[10:11], v[0:1], v[8:9]
	v_pk_fma_f32 v[8:9], v[0:1], v[8:9], v[0:1] neg_lo:[1,0,0] neg_hi:[1,0,0]
	s_nop 0
	v_cndmask_b32_e32 v1, v9, v11, vcc
	v_cmp_gt_f32_e32 vcc, 0, v0
	s_nop 1
	v_cndmask_b32_e32 v0, v8, v10, vcc
	v_pk_mul_f32 v[0:1], v[4:5], v[0:1]
	v_cmp_gt_f32_e32 vcc, 0, v3
	v_cvt_pk_bf16_f32 v0, v0, v1
	v_fma_f32 v1, |v2|, s74, 1.0
	v_rcp_f32_e32 v4, v1
	v_fma_f32 v1, |v3|, s74, 1.0
	v_rcp_f32_e32 v5, v1
	v_mul_f32_e32 v1, v2, v2
	v_mul_f32_e32 v1, 0xbf38aa3b, v1
	v_exp_f32_e32 v8, v1
	v_mul_f32_e32 v1, v3, v3
	v_pk_fma_f32 v[10:11], v[4:5], s[14:15], v[12:13] op_sel_hi:[1,0,0]
	v_mul_f32_e32 v1, 0xbf38aa3b, v1
	v_exp_f32_e32 v9, v1
	v_pk_fma_f32 v[10:11], v[4:5], v[10:11], s[16:17] op_sel_hi:[1,1,0]
	s_movk_i32 s14, 0x1600
	v_pk_fma_f32 v[10:11], v[4:5], v[10:11], s[18:19] op_sel_hi:[1,1,0]
	s_nop 0
	v_pk_fma_f32 v[10:11], v[4:5], v[10:11], s[8:9] op_sel_hi:[1,1,0]
	s_nop 0
	v_pk_mul_f32 v[4:5], v[4:5], v[10:11]
	s_nop 0
	v_pk_mul_f32 v[4:5], v[8:9], v[4:5]
	s_nop 0
	v_pk_mul_f32 v[8:9], v[2:3], v[4:5]
	v_pk_fma_f32 v[4:5], v[2:3], v[4:5], v[2:3] neg_lo:[1,0,0] neg_hi:[1,0,0]
	s_nop 0
	v_cndmask_b32_e32 v3, v5, v9, vcc
	v_cmp_gt_f32_e32 vcc, 0, v2
	s_nop 1
	v_cndmask_b32_e32 v2, v4, v8, vcc
	v_pk_mul_f32 v[2:3], v[6:7], v[2:3]
	s_nop 0
	v_cvt_pk_bf16_f32 v1, v2, v3
	v_mov_b64_e32 v[2:3], s[26:27]
	v_mad_i64_i32 v[2:3], s[14:15], v146, s14, v[2:3]
	v_lshl_add_u64 v[2:3], v[152:153], 1, v[2:3]
	global_store_dwordx2 v[2:3], v[0:1], off offset:8

.LBB0_846:
	s_cmp_lt_i32 s66, s35
	s_cselect_b64 s[14:15], -1, 0
	s_cmp_ge_i32 s66, s24
	s_cselect_b64 s[16:17], -1, 0
	v_pk_fma_f32 v[4:5], v[72:73], v[28:29], v[4:5]
	s_and_b64 s[14:15], s[14:15], s[16:17]
	v_pk_fma_f32 v[6:7], v[74:75], v[30:31], v[6:7]
	v_pk_add_f32 v[4:5], v[76:77], v[4:5]
	v_pk_fma_f32 v[0:1], v[64:65], v[24:25], v[0:1]
	v_pk_add_f32 v[6:7], v[78:79], v[6:7]
	v_pk_fma_f32 v[2:3], v[66:67], v[26:27], v[2:3]
	v_pk_add_f32 v[0:1], v[68:69], v[0:1]
	v_pk_add_f32 v[2:3], v[70:71], v[2:3]
	s_mov_b32 s16, 0x3f35f0e3
	s_mov_b32 s18, 0xbe11a98e
	s_mov_b32 s8, 0x3e027906
	s_cmp_eq_u64 s[14:15], 0
	s_cbranch_scc1 .Lffe_846
	v_cmp_eq_u32_e32 vcc, s37, v134
	v_pk_fma_f32 v[10:11], v[72:73], v[28:29], v[4:5] neg_lo:[1,0,0] neg_hi:[1,0,0]
	s_nop 0
	s_and_b64 vcc, s[14:15], vcc
	v_pk_fma_f32 v[8:9], v[58:59], v[30:31], v[6:7]
	v_cndmask_b32_e32 v5, v5, v11, vcc
	v_cndmask_b32_e32 v4, v4, v10, vcc
	v_pk_fma_f32 v[10:11], v[64:65], v[24:25], v[0:1] neg_lo:[1,0,0] neg_hi:[1,0,0]
	v_cndmask_b32_e32 v7, v7, v9, vcc
	v_cndmask_b32_e32 v6, v6, v8, vcc
	v_pk_fma_f32 v[8:9], v[56:57], v[26:27], v[2:3]
	v_cndmask_b32_e32 v1, v1, v11, vcc
	v_cndmask_b32_e32 v0, v0, v10, vcc
	v_cndmask_b32_e32 v3, v3, v9, vcc
	v_cndmask_b32_e32 v2, v2, v8, vcc
.Lffe_846:
	v_fma_f32 v8, |v0|, s74, 1.0
	v_fma_f32 v9, |v1|, s74, 1.0
	v_rcp_f32_e32 v8, v8
	v_rcp_f32_e32 v9, v9
	s_mov_b32 s14, 0xbf3a00e3
	v_mul_f32_e32 v10, v0, v0
	v_mov_b64_e32 v[12:13], s[14:15]
	s_mov_b32 s14, 0x3f07dc22
	v_mul_f32_e32 v11, v1, v1
	v_mul_f32_e32 v10, 0xbf38aa3b, v10
	v_pk_fma_f32 v[14:15], v[8:9], s[14:15], v[12:13] op_sel_hi:[1,0,0]
	v_mul_f32_e32 v11, 0xbf38aa3b, v11
	v_exp_f32_e32 v10, v10
	v_exp_f32_e32 v11, v11
	v_pk_fma_f32 v[14:15], v[8:9], v[14:15], s[16:17] op_sel_hi:[1,1,0]
	s_nop 0
	v_pk_fma_f32 v[14:15], v[8:9], v[14:15], s[18:19] op_sel_hi:[1,1,0]
	s_nop 0
	v_pk_fma_f32 v[14:15], v[8:9], v[14:15], s[8:9] op_sel_hi:[1,1,0]
	v_cmp_gt_f32_e32 vcc, 0, v1
	v_pk_mul_f32 v[8:9], v[8:9], v[14:15]
	s_nop 0
	v_pk_mul_f32 v[8:9], v[10:11], v[8:9]
	s_nop 0
	v_pk_mul_f32 v[10:11], v[0:1], v[8:9]
	v_pk_fma_f32 v[8:9], v[0:1], v[8:9], v[0:1] neg_lo:[1,0,0] neg_hi:[1,0,0]
	s_nop 0
	v_cndmask_b32_e32 v1, v9, v11, vcc
	v_cmp_gt_f32_e32 vcc, 0, v0
	s_nop 1
	v_cndmask_b32_e32 v0, v8, v10, vcc
	v_pk_mul_f32 v[0:1], v[4:5], v[0:1]
	v_cmp_gt_f32_e32 vcc, 0, v3
	v_cvt_pk_bf16_f32 v0, v0, v1
	v_fma_f32 v1, |v2|, s74, 1.0
	v_rcp_f32_e32 v4, v1
	v_fma_f32 v1, |v3|, s74, 1.0
	v_rcp_f32_e32 v5, v1
	v_mul_f32_e32 v1, v2, v2
	v_mul_f32_e32 v1, 0xbf38aa3b, v1
	v_exp_f32_e32 v8, v1
	v_mul_f32_e32 v1, v3, v3
	v_pk_fma_f32 v[10:11], v[4:5], s[14:15], v[12:13] op_sel_hi:[1,0,0]
	v_mul_f32_e32 v1, 0xbf38aa3b, v1
	v_exp_f32_e32 v9, v1
	v_pk_fma_f32 v[10:11], v[4:5], v[10:11], s[16:17] op_sel_hi:[1,1,0]
	s_movk_i32 s14, 0x1600
	v_pk_fma_f32 v[10:11], v[4:5], v[10:11], s[18:19] op_sel_hi:[1,1,0]
	s_nop 0
	v_pk_fma_f32 v[10:11], v[4:5], v[10:11], s[8:9] op_sel_hi:[1,1,0]
	s_nop 0
	v_pk_mul_f32 v[4:5], v[4:5], v[10:11]
	s_nop 0
	v_pk_mul_f32 v[4:5], v[8:9], v[4:5]
	s_nop 0
	v_pk_mul_f32 v[8:9], v[2:3], v[4:5]
	v_pk_fma_f32 v[4:5], v[2:3], v[4:5], v[2:3] neg_lo:[1,0,0] neg_hi:[1,0,0]
	s_nop 0
	v_cndmask_b32_e32 v3, v5, v9, vcc
	v_cmp_gt_f32_e32 vcc, 0, v2
	s_nop 1
	v_cndmask_b32_e32 v2, v4, v8, vcc
	v_pk_mul_f32 v[2:3], v[6:7], v[2:3]
	s_nop 0
	v_cvt_pk_bf16_f32 v1, v2, v3
	v_mov_b64_e32 v[2:3], s[26:27]
	v_mad_i64_i32 v[2:3], s[14:15], v124, s14, v[2:3]
	v_lshl_add_u64 v[2:3], v[152:153], 1, v[2:3]
	global_store_dwordx2 v[2:3], v[0:1], off offset:8
	s_or_b64 exec, exec, s[12:13]
	s_andn2_b64 vcc, exec, s[46:47]
	s_mov_b64 s[12:13], -1
	s_cbranch_vccnz .LBB0_736

	.amdhsa_kernel _Z4mega6Params
		.amdhsa_group_segment_fixed_size 0
		.amdhsa_private_segment_fixed_size 0
		.amdhsa_kernarg_size 480
		.amdhsa_user_sgpr_count 2
		.amdhsa_user_sgpr_dispatch_ptr 0
		.amdhsa_user_sgpr_queue_ptr 0
		.amdhsa_user_sgpr_kernarg_segment_ptr 1
		.amdhsa_user_sgpr_dispatch_id 0
		.amdhsa_user_sgpr_kernarg_preload_length 0
		.amdhsa_user_sgpr_kernarg_preload_offset 0
		.amdhsa_user_sgpr_private_segment_size 0
		.amdhsa_uses_dynamic_stack 0
		.amdhsa_enable_private_segment 0
		.amdhsa_system_sgpr_workgroup_id_x 1
		.amdhsa_system_sgpr_workgroup_id_y 0
		.amdhsa_system_sgpr_workgroup_id_z 0
		.amdhsa_system_sgpr_workgroup_info 0
		.amdhsa_system_vgpr_workitem_id 2
		.amdhsa_next_free_vgpr 243
		.amdhsa_next_free_sgpr 102
		.amdhsa_accum_offset 244
		.amdhsa_reserve_vcc 1
		.amdhsa_float_round_mode_32 0
		.amdhsa_float_round_mode_16_64 0
		.amdhsa_float_denorm_mode_32 3
		.amdhsa_float_denorm_mode_16_64 3
		.amdhsa_dx10_clamp 1
		.amdhsa_ieee_mode 1
		.amdhsa_fp16_overflow 0
		.amdhsa_tg_split 0
		.amdhsa_exception_fp_ieee_invalid_op 0
		.amdhsa_exception_fp_denorm_src 0
		.amdhsa_exception_fp_ieee_div_zero 0
		.amdhsa_exception_fp_ieee_overflow 0
		.amdhsa_exception_fp_ieee_underflow 0
		.amdhsa_exception_fp_ieee_inexact 0
		.amdhsa_exception_int_div_zero 0
	.end_amdhsa_kernel

.Lfunc_end0:
	.size	_Z4mega6Params, .Lfunc_end0-_Z4mega6Params
	.set _Z4mega6Params.num_vgpr, 243
	.set _Z4mega6Params.num_agpr, 0
	.set _Z4mega6Params.numbered_sgpr, 102
	.set _Z4mega6Params.num_named_barrier, 0
	.set _Z4mega6Params.private_seg_size, 0
	.set _Z4mega6Params.uses_vcc, 1
	.set _Z4mega6Params.uses_flat_scratch, 0
	.set _Z4mega6Params.has_dyn_sized_stack, 0
	.set _Z4mega6Params.has_recursion, 0
	.set _Z4mega6Params.has_indirect_call, 0

amdhsa.kernels:
  - .agpr_count:     0
    .args:
      - .offset:         0
        .size:           224
        .value_kind:     by_value
      - .offset:         224
        .size:           4
        .value_kind:     hidden_block_count_x
      - .offset:         228
        .size:           4
        .value_kind:     hidden_block_count_y
      - .offset:         232
        .size:           4
        .value_kind:     hidden_block_count_z
      - .offset:         236
        .size:           2
        .value_kind:     hidden_group_size_x
      - .offset:         238
        .size:           2
        .value_kind:     hidden_group_size_y
      - .offset:         240
        .size:           2
        .value_kind:     hidden_group_size_z
      - .offset:         242
        .size:           2
        .value_kind:     hidden_remainder_x
      - .offset:         244
        .size:           2
        .value_kind:     hidden_remainder_y
      - .offset:         246
        .size:           2
        .value_kind:     hidden_remainder_z
      - .offset:         264
        .size:           8
        .value_kind:     hidden_global_offset_x
      - .offset:         272
        .size:           8
        .value_kind:     hidden_global_offset_y
      - .offset:         280
        .size:           8
        .value_kind:     hidden_global_offset_z
      - .offset:         288
        .size:           2
        .value_kind:     hidden_grid_dims
      - .offset:         312
        .size:           8
        .value_kind:     hidden_multigrid_sync_arg
      - .offset:         344
        .size:           4
        .value_kind:     hidden_dynamic_lds_size
    .group_segment_fixed_size: 0
    .kernarg_segment_align: 8
    .kernarg_segment_size: 480
    .language:       OpenCL C
    .language_version:
      - 2
      - 0
    .max_flat_workgroup_size: 512
    .name:           _Z4mega6Params
    .private_segment_fixed_size: 0
    .sgpr_count:     108
    .sgpr_spill_count: 37
    .symbol:         _Z4mega6Params.kd
    .uniform_work_group_size: 1
    .uses_dynamic_stack: false
    .vgpr_count:     243
    .vgpr_spill_count: 0
    .wavefront_size: 64
